# attention: split 150 plain v_pk_add_f32 (row-sum chains beside MFMAs) into scalar v_add_f32 pairs, bit-identical
# baseline (speedup 1.0000x reference)
; __device__ __forceinline__ unsigned cvtpk_s(float lo, float hi) { f32x2 v = {lo, hi}; bf16x2_t b = __builtin_convertvector(v, bf16x2_t); return __builtin_bit_cast(unsigned, b); }
; __device__ __forceinline__ void softmax_tail(f32x16& s, HState& S, u32x4 (&pw)[2]) {
;     const float mn = S.m;
; #pragma unroll
;     for (int r = 0; r < 16; ++r) s[r] -= mn;
; #pragma unroll
;     for (int r = 0; r < 16; ++r) s[r] = __builtin_amdgcn_exp2f(s[r]);
;     float p0 = s[0], p1 = s[1];
; #pragma unroll
;     for (int r = 2; r < 16; r += 2) { p0 += s[r]; p1 += s[r + 1]; }
;     S.l += p0 + p1;
; #pragma unroll
;     for (int ks = 0; ks < 2; ++ks) { pw[ks].x = cvtpk_s(s[8 * ks + 0], s[8 * ks + 1]); pw[ks].y = cvtpk_s(s[8 * ks + 2], s[8 * ks + 3]); pw[ks].z = cvtpk_s(s[8 * ks + 4], s[8 * ks + 5]); pw[ks].w = cvtpk_s(s[8 * ks + 6], s[8 * ks + 7]); }
; }
.LBB0_438:
	v_sub_f32_e32 v15, v80, v184
	v_sub_f32_e32 v80, v81, v184
	v_sub_f32_e32 v81, v82, v184
	v_sub_f32_e32 v82, v83, v184
	v_sub_f32_e32 v83, v84, v184
	v_sub_f32_e32 v84, v85, v184
	v_sub_f32_e32 v85, v86, v184
	v_sub_f32_e32 v86, v87, v184
	v_sub_f32_e32 v87, v88, v184
	v_sub_f32_e32 v88, v89, v184
	v_sub_f32_e32 v89, v90, v184
	v_sub_f32_e32 v90, v91, v184
	v_sub_f32_e32 v91, v92, v184
	v_sub_f32_e32 v92, v93, v184
	v_sub_f32_e32 v93, v94, v184
	v_sub_f32_e32 v94, v95, v184
	v_exp_f32_e32 v15, v15
	v_exp_f32_e32 v95, v80
	v_exp_f32_e32 v148, v81
	v_exp_f32_e32 v149, v82
	v_exp_f32_e32 v150, v83
	v_exp_f32_e32 v151, v84
	v_exp_f32_e32 v152, v85
	v_exp_f32_e32 v153, v86
	v_exp_f32_e32 v80, v87
	v_exp_f32_e32 v81, v88
	v_exp_f32_e32 v82, v89
	v_exp_f32_e32 v83, v90
	v_add_f32_e32 v88, v15, v148
	v_add_f32_e32 v89, v95, v149
	v_exp_f32_e32 v84, v91
	v_exp_f32_e32 v85, v92
	v_add_f32_e32 v88, v150, v88
	v_add_f32_e32 v89, v151, v89
	v_exp_f32_e32 v86, v93
	v_exp_f32_e32 v87, v94
	v_add_f32_e32 v88, v152, v88
	v_add_f32_e32 v89, v153, v89
	v_add_f32_e32 v88, v80, v88
	v_add_f32_e32 v89, v81, v89
	v_add_f32_e32 v88, v82, v88
	v_add_f32_e32 v89, v83, v89
	v_add_f32_e32 v88, v84, v88
	v_add_f32_e32 v89, v85, v89
	v_add_f32_e32 v88, v86, v88
	v_add_f32_e32 v89, v87, v89
	v_add_f32_e32 v88, v88, v89
	v_add_f32_e32 v197, v14, v88
	v_cvt_pk_bf16_f32 v80, v80, v81
	v_cvt_pk_bf16_f32 v81, v82, v83
	v_cvt_pk_bf16_f32 v82, v84, v85
	v_cvt_pk_bf16_f32 v83, v86, v87
	v_cvt_pk_bf16_f32 v84, v15, v95
	v_cvt_pk_bf16_f32 v85, v148, v149
	v_cvt_pk_bf16_f32 v86, v150, v151
	v_cvt_pk_bf16_f32 v87, v152, v153
	s_nop 1
	v_mfma_f32_32x32x16_bf16 v[64:79], v[6:9], v[84:87], v[64:79]
	v_sub_f32_e32 v14, v96, v183
	v_sub_f32_e32 v15, v97, v183
	v_sub_f32_e32 v92, v104, v183
	v_sub_f32_e32 v93, v105, v183
	v_sub_f32_e32 v94, v106, v183
	v_sub_f32_e32 v95, v107, v183
	v_sub_f32_e32 v96, v108, v183
	v_sub_f32_e32 v97, v109, v183
	v_mfma_f32_32x32x16_bf16 v[48:63], v[10:13], v[84:87], v[48:63]
	v_sub_f32_e32 v84, v102, v183
	v_sub_f32_e32 v85, v103, v183
	v_exp_f32_e32 v14, v14
	v_exp_f32_e32 v15, v15
	v_exp_f32_e32 v90, v84
	v_exp_f32_e32 v91, v85
	v_exp_f32_e32 v84, v96
	v_mfma_f32_32x32x16_bf16 v[64:79], v[144:147], v[80:83], v[64:79]
	v_exp_f32_e32 v85, v97
	v_mfma_f32_32x32x16_bf16 v[48:63], v[2:5], v[80:83], v[48:63]
	v_sub_f32_e32 v80, v98, v183
	v_sub_f32_e32 v81, v99, v183
	v_sub_f32_e32 v82, v100, v183
	v_sub_f32_e32 v83, v101, v183
	v_exp_f32_e32 v86, v80
	v_exp_f32_e32 v87, v81
	v_exp_f32_e32 v88, v82
	v_exp_f32_e32 v89, v83
	v_exp_f32_e32 v80, v92
	v_exp_f32_e32 v81, v93
	v_exp_f32_e32 v82, v94
	v_exp_f32_e32 v83, v95
	v_add_f32_e32 v94, v14, v86
	v_add_f32_e32 v95, v15, v87
	v_sub_f32_e32 v98, v110, v183
	v_sub_f32_e32 v99, v111, v183
	v_add_f32_e32 v94, v88, v94
	v_add_f32_e32 v95, v89, v95
	v_exp_f32_e32 v92, v98
	v_exp_f32_e32 v93, v99
	v_add_f32_e32 v94, v90, v94
	v_add_f32_e32 v95, v91, v95
	s_nop 0
	v_add_f32_e32 v94, v80, v94
	v_add_f32_e32 v95, v81, v95
	v_cvt_pk_bf16_f32 v80, v80, v81
	v_add_f32_e32 v94, v82, v94
	v_add_f32_e32 v95, v83, v95
	v_cvt_pk_bf16_f32 v81, v82, v83
	v_add_f32_e32 v94, v84, v94
	v_add_f32_e32 v95, v85, v95
	v_cvt_pk_bf16_f32 v82, v84, v85
	v_add_f32_e32 v94, v92, v94
	v_add_f32_e32 v95, v93, v95
	v_cvt_pk_bf16_f32 v83, v92, v93
	v_add_f32_e32 v94, v94, v95
	v_add_f32_e32 v185, v0, v94
	v_cvt_pk_bf16_f32 v84, v14, v15
	v_cvt_pk_bf16_f32 v85, v86, v87
	v_cvt_pk_bf16_f32 v86, v88, v89
	v_cvt_pk_bf16_f32 v87, v90, v91
	s_nop 1
	v_mfma_f32_32x32x16_bf16 v[32:47], v[6:9], v[84:87], v[32:47]
	s_add_i32 s12, s12, 64
	s_cmp_lt_u32 s11, s19
	v_mfma_f32_32x32x16_bf16 v[16:31], v[10:13], v[84:87], v[16:31]
	v_mfma_f32_32x32x16_bf16 v[32:47], v[144:147], v[80:83], v[32:47]
	v_mfma_f32_32x32x16_bf16 v[16:31], v[2:5], v[80:83], v[16:31]
	s_cbranch_scc0 .LBB0_441
	s_mov_b32 s11, s36
	s_branch .LBB0_422

; __device__ __forceinline__ unsigned cvtpk_s(float lo, float hi) { f32x2 v = {lo, hi}; bf16x2_t b = __builtin_convertvector(v, bf16x2_t); return __builtin_bit_cast(unsigned, b); }
; __device__ __forceinline__ void softmax_tail(f32x16& s, HState& S, u32x4 (&pw)[2]) {
;     const float mn = S.m;
; #pragma unroll
;     for (int r = 0; r < 16; ++r) s[r] -= mn;
; #pragma unroll
;     for (int r = 0; r < 16; ++r) s[r] = __builtin_amdgcn_exp2f(s[r]);
;     float p0 = s[0], p1 = s[1];
; #pragma unroll
;     for (int r = 2; r < 16; r += 2) { p0 += s[r]; p1 += s[r + 1]; }
;     S.l += p0 + p1;
; #pragma unroll
;     for (int ks = 0; ks < 2; ++ks) { pw[ks].x = cvtpk_s(s[8 * ks + 0], s[8 * ks + 1]); pw[ks].y = cvtpk_s(s[8 * ks + 2], s[8 * ks + 3]); pw[ks].z = cvtpk_s(s[8 * ks + 4], s[8 * ks + 5]); pw[ks].w = cvtpk_s(s[8 * ks + 6], s[8 * ks + 7]); }
; }
; __device__ __forceinline__ void softmax_tile(f32x16& s, int kb, int lq, int radius, bool full, int hi, HState& S, u32x4 (&pw)[2]) { softmax_head(s, kb, lq, radius, full, hi, S); softmax_tail(s, S, pw); }
; __device__ __forceinline__ void pv_tile(const bf16x8 (&vf)[2][2], const u32x4 (&pw)[2], HState& S) {
; #pragma unroll
;     for (int ks = 0; ks < 2; ++ks)
; #pragma unroll
;         for (int dh = 0; dh < 2; ++dh) S.o[dh] = __builtin_amdgcn_mfma_f32_32x32x16_bf16(vf[ks][dh], __builtin_bit_cast(bf16x8, pw[ks]), S.o[dh], 0, 0, 0);
.LBB0_451:
	v_sub_f32_e32 v14, v80, v184
	v_sub_f32_e32 v15, v81, v184
	v_sub_f32_e32 v80, v82, v184
	v_sub_f32_e32 v81, v83, v184
	v_sub_f32_e32 v82, v84, v184
	v_sub_f32_e32 v83, v85, v184
	v_sub_f32_e32 v84, v86, v184
	v_sub_f32_e32 v85, v87, v184
	v_sub_f32_e32 v86, v88, v184
	v_sub_f32_e32 v87, v89, v184
	v_sub_f32_e32 v88, v90, v184
	v_sub_f32_e32 v89, v91, v184
	v_sub_f32_e32 v90, v92, v184
	v_sub_f32_e32 v91, v93, v184
	v_sub_f32_e32 v92, v94, v184
	v_sub_f32_e32 v93, v95, v184
	v_exp_f32_e32 v14, v14
	v_exp_f32_e32 v15, v15
	v_exp_f32_e32 v94, v80
	v_exp_f32_e32 v95, v81
	v_exp_f32_e32 v116, v82
	v_exp_f32_e32 v117, v83
	v_exp_f32_e32 v118, v84
	v_exp_f32_e32 v119, v85
	v_exp_f32_e32 v80, v86
	v_exp_f32_e32 v81, v87
	v_exp_f32_e32 v82, v88
	v_exp_f32_e32 v83, v89
	v_add_f32_e32 v88, v14, v94
	v_add_f32_e32 v89, v15, v95
	v_exp_f32_e32 v84, v90
	v_exp_f32_e32 v85, v91
	v_add_f32_e32 v88, v116, v88
	v_add_f32_e32 v89, v117, v89
	v_exp_f32_e32 v86, v92
	v_exp_f32_e32 v87, v93
	v_add_f32_e32 v88, v118, v88
	v_add_f32_e32 v89, v119, v89
	v_add_f32_e32 v88, v80, v88
	v_add_f32_e32 v89, v81, v89
	v_add_f32_e32 v88, v82, v88
	v_add_f32_e32 v89, v83, v89
	v_add_f32_e32 v88, v84, v88
	v_add_f32_e32 v89, v85, v89
	v_add_f32_e32 v88, v86, v88
	v_add_f32_e32 v89, v87, v89
	v_add_f32_e32 v88, v88, v89
	v_add_f32_e32 v197, v197, v88
	v_cvt_pk_bf16_f32 v80, v80, v81
	v_cvt_pk_bf16_f32 v81, v82, v83
	v_cvt_pk_bf16_f32 v82, v84, v85
	v_cvt_pk_bf16_f32 v83, v86, v87
	v_cvt_pk_bf16_f32 v84, v14, v15
	v_cvt_pk_bf16_f32 v85, v94, v95
	v_cvt_pk_bf16_f32 v86, v116, v117
	v_cvt_pk_bf16_f32 v87, v118, v119
	s_nop 1
	v_mfma_f32_32x32x16_bf16 v[64:79], v[2:5], v[84:87], v[64:79]
	v_sub_f32_e32 v14, v96, v183
	v_sub_f32_e32 v15, v97, v183
	v_sub_f32_e32 v92, v104, v183
	v_sub_f32_e32 v93, v105, v183
	v_sub_f32_e32 v94, v106, v183
	v_sub_f32_e32 v95, v107, v183
	v_sub_f32_e32 v96, v108, v183
	v_sub_f32_e32 v97, v109, v183
	v_mfma_f32_32x32x16_bf16 v[48:63], v[6:9], v[84:87], v[48:63]
	v_sub_f32_e32 v84, v102, v183
	v_sub_f32_e32 v85, v103, v183
	v_exp_f32_e32 v14, v14
	v_exp_f32_e32 v15, v15
	v_exp_f32_e32 v90, v84
	v_exp_f32_e32 v91, v85
	v_exp_f32_e32 v84, v96
	v_mfma_f32_32x32x16_bf16 v[64:79], v[10:13], v[80:83], v[64:79]
	v_exp_f32_e32 v85, v97
	v_mfma_f32_32x32x16_bf16 v[48:63], v[112:115], v[80:83], v[48:63]
	v_sub_f32_e32 v80, v98, v183
	v_sub_f32_e32 v81, v99, v183
	v_sub_f32_e32 v82, v100, v183
	v_sub_f32_e32 v83, v101, v183
	v_exp_f32_e32 v86, v80
	v_exp_f32_e32 v87, v81
	v_exp_f32_e32 v88, v82
	v_exp_f32_e32 v89, v83
	v_exp_f32_e32 v80, v92
	v_exp_f32_e32 v81, v93
	v_exp_f32_e32 v82, v94
	v_exp_f32_e32 v83, v95
	v_add_f32_e32 v94, v14, v86
	v_add_f32_e32 v95, v15, v87
	v_sub_f32_e32 v98, v110, v183
	v_sub_f32_e32 v99, v111, v183
	v_add_f32_e32 v94, v88, v94
	v_add_f32_e32 v95, v89, v95
	v_exp_f32_e32 v92, v98
	v_exp_f32_e32 v93, v99
	v_add_f32_e32 v94, v90, v94
	v_add_f32_e32 v95, v91, v95
	s_nop 0
	v_add_f32_e32 v94, v80, v94
	v_add_f32_e32 v95, v81, v95
	v_cvt_pk_bf16_f32 v80, v80, v81
	v_add_f32_e32 v94, v82, v94
	v_add_f32_e32 v95, v83, v95
	v_cvt_pk_bf16_f32 v81, v82, v83
	v_add_f32_e32 v94, v84, v94
	v_add_f32_e32 v95, v85, v95
	v_cvt_pk_bf16_f32 v82, v84, v85
	v_add_f32_e32 v94, v92, v94
	v_add_f32_e32 v95, v93, v95
	v_cvt_pk_bf16_f32 v83, v92, v93
	v_add_f32_e32 v94, v94, v95
	v_add_f32_e32 v185, v185, v94
	v_cvt_pk_bf16_f32 v84, v14, v15
	v_cvt_pk_bf16_f32 v85, v86, v87
	v_cvt_pk_bf16_f32 v86, v88, v89
	v_cvt_pk_bf16_f32 v87, v90, v91
	s_nop 1
	v_mfma_f32_32x32x16_bf16 v[32:47], v[2:5], v[84:87], v[32:47]
	v_mfma_f32_32x32x16_bf16 v[16:31], v[6:9], v[84:87], v[16:31]
	v_mfma_f32_32x32x16_bf16 v[32:47], v[10:13], v[80:83], v[32:47]
	v_mfma_f32_32x32x16_bf16 v[16:31], v[112:115], v[80:83], v[16:31]

; __device__ __forceinline__ unsigned cvtpk_s(float lo, float hi) { f32x2 v = {lo, hi}; bf16x2_t b = __builtin_convertvector(v, bf16x2_t); return __builtin_bit_cast(unsigned, b); }
; __device__ __forceinline__ void softmax_tail(f32x16& s, HState& S, u32x4 (&pw)[2]) {
;     const float mn = S.m;
; #pragma unroll
;     for (int r = 0; r < 16; ++r) s[r] -= mn;
; #pragma unroll
;     for (int r = 0; r < 16; ++r) s[r] = __builtin_amdgcn_exp2f(s[r]);
;     float p0 = s[0], p1 = s[1];
; #pragma unroll
;     for (int r = 2; r < 16; r += 2) { p0 += s[r]; p1 += s[r + 1]; }
;     S.l += p0 + p1;
; #pragma unroll
;     for (int ks = 0; ks < 2; ++ks) { pw[ks].x = cvtpk_s(s[8 * ks + 0], s[8 * ks + 1]); pw[ks].y = cvtpk_s(s[8 * ks + 2], s[8 * ks + 3]); pw[ks].z = cvtpk_s(s[8 * ks + 4], s[8 * ks + 5]); pw[ks].w = cvtpk_s(s[8 * ks + 6], s[8 * ks + 7]); }
; }
; __device__ __forceinline__ void softmax_tile(f32x16& s, int kb, int lq, int radius, bool full, int hi, HState& S, u32x4 (&pw)[2]) { softmax_head(s, kb, lq, radius, full, hi, S); softmax_tail(s, S, pw); }
; __device__ __forceinline__ void pv_tile(const bf16x8 (&vf)[2][2], const u32x4 (&pw)[2], HState& S) {
; #pragma unroll
;     for (int ks = 0; ks < 2; ++ks)
; #pragma unroll
;         for (int dh = 0; dh < 2; ++dh) S.o[dh] = __builtin_amdgcn_mfma_f32_32x32x16_bf16(vf[ks][dh], __builtin_bit_cast(bf16x8, pw[ks]), S.o[dh], 0, 0, 0);
.LBB0_513:
	v_sub_f32_e32 v0, v80, v168
	v_sub_f32_e32 v14, v81, v168
	v_sub_f32_e32 v15, v82, v168
	v_sub_f32_e32 v80, v83, v168
	v_sub_f32_e32 v81, v84, v168
	v_sub_f32_e32 v82, v85, v168
	v_sub_f32_e32 v84, v87, v168
	v_sub_f32_e32 v87, v90, v168
	v_sub_f32_e32 v90, v93, v168
	v_exp_f32_e32 v0, v0
	v_exp_f32_e32 v14, v14
	v_exp_f32_e32 v15, v15
	v_exp_f32_e32 v93, v80
	v_sub_f32_e32 v83, v86, v168
	v_sub_f32_e32 v85, v88, v168
	v_sub_f32_e32 v86, v89, v168
	v_sub_f32_e32 v88, v91, v168
	v_sub_f32_e32 v89, v92, v168
	v_sub_f32_e32 v91, v94, v168
	v_sub_f32_e32 v92, v95, v168
	v_exp_f32_e32 v94, v81
	v_exp_f32_e32 v95, v82
	v_exp_f32_e32 v116, v83
	v_exp_f32_e32 v117, v84
	v_exp_f32_e32 v80, v85
	v_exp_f32_e32 v81, v86
	v_exp_f32_e32 v82, v87
	v_exp_f32_e32 v83, v88
	v_exp_f32_e32 v84, v89
	v_add_f32_e32 v88, v0, v15
	v_add_f32_e32 v89, v14, v93
	v_exp_f32_e32 v85, v90
	v_add_f32_e32 v88, v94, v88
	v_add_f32_e32 v89, v95, v89
	v_exp_f32_e32 v86, v91
	v_exp_f32_e32 v87, v92
	v_add_f32_e32 v88, v116, v88
	v_add_f32_e32 v89, v117, v89
	v_add_f32_e32 v88, v80, v88
	v_add_f32_e32 v89, v81, v89
	v_add_f32_e32 v88, v82, v88
	v_add_f32_e32 v89, v83, v89
	v_add_f32_e32 v88, v84, v88
	v_add_f32_e32 v89, v85, v89
	v_add_f32_e32 v88, v86, v88
	v_add_f32_e32 v89, v87, v89
	v_add_f32_e32 v88, v88, v89
	v_add_f32_e32 v175, v175, v88
	v_cvt_pk_bf16_f32 v80, v80, v81
	v_cvt_pk_bf16_f32 v81, v82, v83
	v_cvt_pk_bf16_f32 v82, v84, v85
	v_cvt_pk_bf16_f32 v83, v86, v87
	v_cvt_pk_bf16_f32 v84, v0, v14
	v_cvt_pk_bf16_f32 v85, v15, v93
	v_cvt_pk_bf16_f32 v86, v94, v95
	v_cvt_pk_bf16_f32 v87, v116, v117
	s_nop 1
	v_mfma_f32_32x32x16_bf16 v[64:79], v[2:5], v[84:87], v[64:79]
	v_sub_f32_e32 v0, v96, v169
	v_sub_f32_e32 v15, v97, v169
	v_sub_f32_e32 v92, v104, v169
	v_sub_f32_e32 v93, v105, v169
	v_sub_f32_e32 v94, v106, v169
	v_sub_f32_e32 v95, v107, v169
	v_sub_f32_e32 v96, v108, v169
	v_sub_f32_e32 v97, v109, v169
	v_mfma_f32_32x32x16_bf16 v[48:63], v[6:9], v[84:87], v[48:63]
	v_sub_f32_e32 v84, v102, v169
	v_sub_f32_e32 v85, v103, v169
	v_exp_f32_e32 v14, v0
	v_exp_f32_e32 v15, v15
	v_exp_f32_e32 v90, v84
	v_exp_f32_e32 v91, v85
	v_exp_f32_e32 v84, v96
	v_mfma_f32_32x32x16_bf16 v[64:79], v[10:13], v[80:83], v[64:79]
	v_exp_f32_e32 v85, v97
	v_mfma_f32_32x32x16_bf16 v[48:63], v[112:115], v[80:83], v[48:63]
	v_sub_f32_e32 v80, v98, v169
	v_sub_f32_e32 v81, v99, v169
	v_sub_f32_e32 v82, v100, v169
	v_sub_f32_e32 v83, v101, v169
	v_exp_f32_e32 v86, v80
	v_exp_f32_e32 v87, v81
	v_exp_f32_e32 v88, v82
	v_exp_f32_e32 v89, v83
	v_exp_f32_e32 v80, v92
	v_exp_f32_e32 v81, v93
	v_exp_f32_e32 v82, v94
	v_exp_f32_e32 v83, v95
	v_add_f32_e32 v94, v14, v86
	v_add_f32_e32 v95, v15, v87
	v_sub_f32_e32 v98, v110, v169
	v_sub_f32_e32 v99, v111, v169
	v_add_f32_e32 v94, v88, v94
	v_add_f32_e32 v95, v89, v95
	v_exp_f32_e32 v92, v98
	v_exp_f32_e32 v93, v99
	v_add_f32_e32 v94, v90, v94
	v_add_f32_e32 v95, v91, v95
	s_nop 0
	v_add_f32_e32 v94, v80, v94
	v_add_f32_e32 v95, v81, v95
	v_cvt_pk_bf16_f32 v80, v80, v81
	v_add_f32_e32 v94, v82, v94
	v_add_f32_e32 v95, v83, v95
	v_cvt_pk_bf16_f32 v81, v82, v83
	v_add_f32_e32 v94, v84, v94
	v_add_f32_e32 v95, v85, v95
	v_cvt_pk_bf16_f32 v82, v84, v85
	v_add_f32_e32 v94, v92, v94
	v_add_f32_e32 v95, v93, v95
	v_cvt_pk_bf16_f32 v83, v92, v93
	v_add_f32_e32 v0, v94, v95
	v_add_f32_e32 v176, v176, v0
	v_cvt_pk_bf16_f32 v84, v14, v15
	v_cvt_pk_bf16_f32 v85, v86, v87
	v_cvt_pk_bf16_f32 v86, v88, v89
	v_cvt_pk_bf16_f32 v87, v90, v91
	s_nop 1
	v_mfma_f32_32x32x16_bf16 v[32:47], v[2:5], v[84:87], v[32:47]
	v_mfma_f32_32x32x16_bf16 v[16:31], v[6:9], v[84:87], v[16:31]
	v_mfma_f32_32x32x16_bf16 v[32:47], v[10:13], v[80:83], v[32:47]
	v_mfma_f32_32x32x16_bf16 v[16:31], v[112:115], v[80:83], v[16:31]

; __device__ __forceinline__ unsigned cvtpk_s(float lo, float hi) { f32x2 v = {lo, hi}; bf16x2_t b = __builtin_convertvector(v, bf16x2_t); return __builtin_bit_cast(unsigned, b); }
; __device__ __forceinline__ void softmax_tail(f32x16& s, HState& S, u32x4 (&pw)[2]) {
;     const float mn = S.m;
; #pragma unroll
;     for (int r = 0; r < 16; ++r) s[r] -= mn;
; #pragma unroll
;     for (int r = 0; r < 16; ++r) s[r] = __builtin_amdgcn_exp2f(s[r]);
;     float p0 = s[0], p1 = s[1];
; #pragma unroll
;     for (int r = 2; r < 16; r += 2) { p0 += s[r]; p1 += s[r + 1]; }
;     S.l += p0 + p1;
; #pragma unroll
;     for (int ks = 0; ks < 2; ++ks) { pw[ks].x = cvtpk_s(s[8 * ks + 0], s[8 * ks + 1]); pw[ks].y = cvtpk_s(s[8 * ks + 2], s[8 * ks + 3]); pw[ks].z = cvtpk_s(s[8 * ks + 4], s[8 * ks + 5]); pw[ks].w = cvtpk_s(s[8 * ks + 6], s[8 * ks + 7]); }
; }
; __device__ __forceinline__ void softmax_tile(f32x16& s, int kb, int lq, int radius, bool full, int hi, HState& S, u32x4 (&pw)[2]) { softmax_head(s, kb, lq, radius, full, hi, S); softmax_tail(s, S, pw); }
; __device__ __forceinline__ void pv_tile(const bf16x8 (&vf)[2][2], const u32x4 (&pw)[2], HState& S) {
; #pragma unroll
;     for (int ks = 0; ks < 2; ++ks)
; #pragma unroll
;         for (int dh = 0; dh < 2; ++dh) S.o[dh] = __builtin_amdgcn_mfma_f32_32x32x16_bf16(vf[ks][dh], __builtin_bit_cast(bf16x8, pw[ks]), S.o[dh], 0, 0, 0);
.LBB0_533:
	v_sub_f32_e32 v15, v80, v168
	v_sub_f32_e32 v80, v81, v168
	v_sub_f32_e32 v81, v82, v168
	v_sub_f32_e32 v82, v83, v168
	v_sub_f32_e32 v83, v84, v168
	v_sub_f32_e32 v84, v85, v168
	v_sub_f32_e32 v85, v86, v168
	v_sub_f32_e32 v86, v87, v168
	v_sub_f32_e32 v87, v88, v168
	v_sub_f32_e32 v88, v89, v168
	v_sub_f32_e32 v89, v90, v168
	v_sub_f32_e32 v90, v91, v168
	v_sub_f32_e32 v91, v92, v168
	v_sub_f32_e32 v92, v93, v168
	v_sub_f32_e32 v93, v94, v168
	v_sub_f32_e32 v94, v95, v168
	v_exp_f32_e32 v15, v15
	v_exp_f32_e32 v95, v80
	v_exp_f32_e32 v148, v81
	v_exp_f32_e32 v149, v82
	v_exp_f32_e32 v150, v83
	v_exp_f32_e32 v151, v84
	v_exp_f32_e32 v152, v85
	v_exp_f32_e32 v153, v86
	v_exp_f32_e32 v80, v87
	v_exp_f32_e32 v81, v88
	v_exp_f32_e32 v82, v89
	v_exp_f32_e32 v83, v90
	v_add_f32_e32 v88, v15, v148
	v_add_f32_e32 v89, v95, v149
	v_exp_f32_e32 v84, v91
	v_exp_f32_e32 v85, v92
	v_add_f32_e32 v88, v150, v88
	v_add_f32_e32 v89, v151, v89
	v_exp_f32_e32 v86, v93
	v_exp_f32_e32 v87, v94
	v_add_f32_e32 v88, v152, v88
	v_add_f32_e32 v89, v153, v89
	v_add_f32_e32 v88, v80, v88
	v_add_f32_e32 v89, v81, v89
	v_add_f32_e32 v88, v82, v88
	v_add_f32_e32 v89, v83, v89
	v_add_f32_e32 v88, v84, v88
	v_add_f32_e32 v89, v85, v89
	v_add_f32_e32 v88, v86, v88
	v_add_f32_e32 v89, v87, v89
	v_add_f32_e32 v88, v88, v89
	v_add_f32_e32 v175, v14, v88
	v_cvt_pk_bf16_f32 v80, v80, v81
	v_cvt_pk_bf16_f32 v81, v82, v83
	v_cvt_pk_bf16_f32 v82, v84, v85
	v_cvt_pk_bf16_f32 v83, v86, v87
	v_cvt_pk_bf16_f32 v84, v15, v95
	v_cvt_pk_bf16_f32 v85, v148, v149
	v_cvt_pk_bf16_f32 v86, v150, v151
	v_cvt_pk_bf16_f32 v87, v152, v153
	s_nop 1
	v_mfma_f32_32x32x16_bf16 v[64:79], v[6:9], v[84:87], v[64:79]
	v_sub_f32_e32 v14, v96, v169
	v_sub_f32_e32 v15, v97, v169
	v_sub_f32_e32 v92, v104, v169
	v_sub_f32_e32 v93, v105, v169
	v_sub_f32_e32 v94, v106, v169
	v_sub_f32_e32 v95, v107, v169
	v_sub_f32_e32 v96, v108, v169
	v_sub_f32_e32 v97, v109, v169
	v_mfma_f32_32x32x16_bf16 v[48:63], v[10:13], v[84:87], v[48:63]
	v_sub_f32_e32 v84, v102, v169
	v_sub_f32_e32 v85, v103, v169
	v_exp_f32_e32 v14, v14
	v_exp_f32_e32 v15, v15
	v_exp_f32_e32 v90, v84
	v_exp_f32_e32 v91, v85
	v_exp_f32_e32 v84, v96
	v_mfma_f32_32x32x16_bf16 v[64:79], v[144:147], v[80:83], v[64:79]
	v_exp_f32_e32 v85, v97
	v_mfma_f32_32x32x16_bf16 v[48:63], v[2:5], v[80:83], v[48:63]
	v_sub_f32_e32 v80, v98, v169
	v_sub_f32_e32 v81, v99, v169
	v_sub_f32_e32 v82, v100, v169
	v_sub_f32_e32 v83, v101, v169
	v_exp_f32_e32 v86, v80
	v_exp_f32_e32 v87, v81
	v_exp_f32_e32 v88, v82
	v_exp_f32_e32 v89, v83
	v_exp_f32_e32 v80, v92
	v_exp_f32_e32 v81, v93
	v_exp_f32_e32 v82, v94
	v_exp_f32_e32 v83, v95
	v_add_f32_e32 v94, v14, v86
	v_add_f32_e32 v95, v15, v87
	v_sub_f32_e32 v98, v110, v169
	v_sub_f32_e32 v99, v111, v169
	v_add_f32_e32 v94, v88, v94
	v_add_f32_e32 v95, v89, v95
	v_exp_f32_e32 v92, v98
	v_exp_f32_e32 v93, v99
	v_add_f32_e32 v94, v90, v94
	v_add_f32_e32 v95, v91, v95
	s_nop 0
	v_add_f32_e32 v94, v80, v94
	v_add_f32_e32 v95, v81, v95
	v_cvt_pk_bf16_f32 v80, v80, v81
	v_add_f32_e32 v94, v82, v94
	v_add_f32_e32 v95, v83, v95
	v_cvt_pk_bf16_f32 v81, v82, v83
	v_add_f32_e32 v94, v84, v94
	v_add_f32_e32 v95, v85, v95
	v_cvt_pk_bf16_f32 v82, v84, v85
	v_add_f32_e32 v94, v92, v94
	v_add_f32_e32 v95, v93, v95
	v_cvt_pk_bf16_f32 v83, v92, v93
	v_add_f32_e32 v94, v94, v95
	v_add_f32_e32 v176, v0, v94
	v_cvt_pk_bf16_f32 v84, v14, v15
	v_cvt_pk_bf16_f32 v85, v86, v87
	v_cvt_pk_bf16_f32 v86, v88, v89
	v_cvt_pk_bf16_f32 v87, v90, v91
	s_nop 1
	v_mfma_f32_32x32x16_bf16 v[32:47], v[6:9], v[84:87], v[32:47]
	s_add_i32 s43, s43, 64
	v_add_u32_e32 v172, 0x1000, v172
	s_cmp_lt_u32 s44, s38
	v_mfma_f32_32x32x16_bf16 v[16:31], v[10:13], v[84:87], v[16:31]
	v_mfma_f32_32x32x16_bf16 v[32:47], v[144:147], v[80:83], v[32:47]
	v_mfma_f32_32x32x16_bf16 v[16:31], v[2:5], v[80:83], v[16:31]
	s_cbranch_scc0 .LBB0_536
	s_mov_b32 s44, s36
	s_branch .LBB0_517

; __device__ __forceinline__ unsigned cvtpk_s(float lo, float hi) { f32x2 v = {lo, hi}; bf16x2_t b = __builtin_convertvector(v, bf16x2_t); return __builtin_bit_cast(unsigned, b); }
; __device__ __forceinline__ void softmax_tail(f32x16& s, HState& S, u32x4 (&pw)[2]) {
;     const float mn = S.m;
; #pragma unroll
;     for (int r = 0; r < 16; ++r) s[r] -= mn;
; #pragma unroll
;     for (int r = 0; r < 16; ++r) s[r] = __builtin_amdgcn_exp2f(s[r]);
;     float p0 = s[0], p1 = s[1];
; #pragma unroll
;     for (int r = 2; r < 16; r += 2) { p0 += s[r]; p1 += s[r + 1]; }
;     S.l += p0 + p1;
; #pragma unroll
;     for (int ks = 0; ks < 2; ++ks) { pw[ks].x = cvtpk_s(s[8 * ks + 0], s[8 * ks + 1]); pw[ks].y = cvtpk_s(s[8 * ks + 2], s[8 * ks + 3]); pw[ks].z = cvtpk_s(s[8 * ks + 4], s[8 * ks + 5]); pw[ks].w = cvtpk_s(s[8 * ks + 6], s[8 * ks + 7]); }
; }
; __device__ __forceinline__ void softmax_tile(f32x16& s, int kb, int lq, int radius, bool full, int hi, HState& S, u32x4 (&pw)[2]) { softmax_head(s, kb, lq, radius, full, hi, S); softmax_tail(s, S, pw); }
; __device__ __forceinline__ void pv_tile(const bf16x8 (&vf)[2][2], const u32x4 (&pw)[2], HState& S) {
; #pragma unroll
;     for (int ks = 0; ks < 2; ++ks)
; #pragma unroll
;         for (int dh = 0; dh < 2; ++dh) S.o[dh] = __builtin_amdgcn_mfma_f32_32x32x16_bf16(vf[ks][dh], __builtin_bit_cast(bf16x8, pw[ks]), S.o[dh], 0, 0, 0);
.LBB0_545:
	v_sub_f32_e32 v0, v80, v185
	v_sub_f32_e32 v15, v81, v185
	v_sub_f32_e32 v80, v82, v185
	v_sub_f32_e32 v81, v83, v185
	v_sub_f32_e32 v82, v84, v185
	v_sub_f32_e32 v83, v85, v185
	v_sub_f32_e32 v100, v86, v185
	v_sub_f32_e32 v101, v87, v185
	v_sub_f32_e32 v102, v88, v185
	v_sub_f32_e32 v103, v89, v185
	v_exp_f32_e32 v14, v0
	v_exp_f32_e32 v15, v15
	v_exp_f32_e32 v84, v80
	v_exp_f32_e32 v85, v81
	v_exp_f32_e32 v86, v82
	v_exp_f32_e32 v87, v83
	v_exp_f32_e32 v88, v100
	v_exp_f32_e32 v89, v101
	v_cvt_pk_bf16_f32 v80, v14, v15
	v_cvt_pk_bf16_f32 v81, v84, v85
	v_cvt_pk_bf16_f32 v82, v86, v87
	v_cvt_pk_bf16_f32 v83, v88, v89
	v_sub_f32_e32 v104, v90, v185
	v_sub_f32_e32 v105, v91, v185
	s_waitcnt lgkmcnt(6)
	v_mfma_f32_32x32x16_bf16 v[32:47], v[96:99], v[80:83], v[32:47]
	v_sub_f32_e32 v106, v92, v185
	v_sub_f32_e32 v107, v93, v185
	v_sub_f32_e32 v108, v94, v185
	v_sub_f32_e32 v109, v95, v185
	v_exp_f32_e32 v90, v102
	v_exp_f32_e32 v91, v103
	v_exp_f32_e32 v92, v104
	s_waitcnt lgkmcnt(4)
	v_mfma_f32_32x32x16_bf16 v[16:31], v[10:13], v[80:83], v[16:31]
	v_exp_f32_e32 v93, v105
	v_exp_f32_e32 v94, v106
	v_exp_f32_e32 v95, v107
	v_exp_f32_e32 v96, v108
	v_exp_f32_e32 v97, v109
	v_add_f32_e32 v10, v14, v84
	v_add_f32_e32 v11, v15, v85
	v_cvt_pk_bf16_f32 v12, v94, v95
	v_add_f32_e32 v14, v86, v10
	v_add_f32_e32 v15, v87, v11
	v_cvt_pk_bf16_f32 v10, v90, v91
	v_cvt_pk_bf16_f32 v11, v92, v93
	v_cvt_pk_bf16_f32 v13, v96, v97
	s_waitcnt lgkmcnt(2)
	s_nop 0
	v_mfma_f32_32x32x16_bf16 v[32:47], v[6:9], v[10:13], v[32:47]
	v_add_f32_e64 v6, v88, v14
	v_add_f32_e64 v7, v89, v15
	v_add_f32_e64 v6, v90, v6
	v_add_f32_e64 v7, v91, v7
	v_add_f32_e64 v6, v92, v6
	v_add_f32_e64 v7, v93, v7
	v_add_f32_e32 v6, v94, v6
	v_add_f32_e32 v7, v95, v7
	s_waitcnt lgkmcnt(0)
	v_mfma_f32_32x32x16_bf16 v[16:31], v[2:5], v[10:13], v[16:31]
	v_add_f32_e64 v6, v96, v6
	v_add_f32_e64 v7, v97, v7
	v_add_f32_e32 v0, v6, v7
	v_add_f32_e32 v186, v186, v0

; __device__ __forceinline__ unsigned cvtpk_s(float lo, float hi) { f32x2 v = {lo, hi}; bf16x2_t b = __builtin_convertvector(v, bf16x2_t); return __builtin_bit_cast(unsigned, b); }
; __device__ __forceinline__ void softmax_tail(f32x16& s, HState& S, u32x4 (&pw)[2]) {
;     const float mn = S.m;
; #pragma unroll
;     for (int r = 0; r < 16; ++r) s[r] -= mn;
; #pragma unroll
;     for (int r = 0; r < 16; ++r) s[r] = __builtin_amdgcn_exp2f(s[r]);
;     float p0 = s[0], p1 = s[1];
; #pragma unroll
;     for (int r = 2; r < 16; r += 2) { p0 += s[r]; p1 += s[r + 1]; }
;     S.l += p0 + p1;
; #pragma unroll
;     for (int ks = 0; ks < 2; ++ks) { pw[ks].x = cvtpk_s(s[8 * ks + 0], s[8 * ks + 1]); pw[ks].y = cvtpk_s(s[8 * ks + 2], s[8 * ks + 3]); pw[ks].z = cvtpk_s(s[8 * ks + 4], s[8 * ks + 5]); pw[ks].w = cvtpk_s(s[8 * ks + 6], s[8 * ks + 7]); }
; }
; __device__ __forceinline__ void softmax_tile(f32x16& s, int kb, int lq, int radius, bool full, int hi, HState& S, u32x4 (&pw)[2]) { softmax_head(s, kb, lq, radius, full, hi, S); softmax_tail(s, S, pw); }
; __device__ __forceinline__ void pv_tile(const bf16x8 (&vf)[2][2], const u32x4 (&pw)[2], HState& S) {
; #pragma unroll
;     for (int ks = 0; ks < 2; ++ks)
; #pragma unroll
;         for (int dh = 0; dh < 2; ++dh) S.o[dh] = __builtin_amdgcn_mfma_f32_32x32x16_bf16(vf[ks][dh], __builtin_bit_cast(bf16x8, pw[ks]), S.o[dh], 0, 0, 0);
.LBB0_564:
	v_sub_f32_e32 v15, v80, v196
	v_sub_f32_e32 v80, v81, v196
	v_sub_f32_e32 v81, v82, v196
	v_sub_f32_e32 v82, v83, v196
	v_sub_f32_e32 v83, v84, v196
	v_sub_f32_e32 v84, v85, v196
	v_sub_f32_e32 v85, v86, v196
	v_sub_f32_e32 v86, v87, v196
	v_sub_f32_e32 v87, v88, v196
	v_sub_f32_e32 v88, v89, v196
	v_sub_f32_e32 v89, v90, v196
	v_sub_f32_e32 v90, v91, v196
	v_sub_f32_e32 v91, v92, v196
	v_sub_f32_e32 v92, v93, v196
	v_sub_f32_e32 v93, v94, v196
	v_sub_f32_e32 v94, v95, v196
	v_exp_f32_e32 v15, v15
	v_exp_f32_e32 v95, v80
	v_exp_f32_e32 v148, v81
	v_exp_f32_e32 v149, v82
	v_exp_f32_e32 v150, v83
	v_exp_f32_e32 v151, v84
	v_exp_f32_e32 v152, v85
	v_exp_f32_e32 v153, v86
	v_exp_f32_e32 v80, v87
	v_exp_f32_e32 v81, v88
	v_exp_f32_e32 v82, v89
	v_exp_f32_e32 v83, v90
	v_add_f32_e32 v88, v15, v148
	v_add_f32_e32 v89, v95, v149
	v_exp_f32_e32 v84, v91
	v_exp_f32_e32 v85, v92
	v_add_f32_e32 v88, v150, v88
	v_add_f32_e32 v89, v151, v89
	v_exp_f32_e32 v86, v93
	v_exp_f32_e32 v87, v94
	v_add_f32_e32 v88, v152, v88
	v_add_f32_e32 v89, v153, v89
	v_add_f32_e32 v88, v80, v88
	v_add_f32_e32 v89, v81, v89
	v_add_f32_e32 v88, v82, v88
	v_add_f32_e32 v89, v83, v89
	v_add_f32_e32 v88, v84, v88
	v_add_f32_e32 v89, v85, v89
	v_add_f32_e32 v88, v86, v88
	v_add_f32_e32 v89, v87, v89
	v_add_f32_e32 v88, v88, v89
	v_add_f32_e32 v207, v14, v88
	v_cvt_pk_bf16_f32 v80, v80, v81
	v_cvt_pk_bf16_f32 v81, v82, v83
	v_cvt_pk_bf16_f32 v82, v84, v85
	v_cvt_pk_bf16_f32 v83, v86, v87
	v_cvt_pk_bf16_f32 v84, v15, v95
	v_cvt_pk_bf16_f32 v85, v148, v149
	v_cvt_pk_bf16_f32 v86, v150, v151
	v_cvt_pk_bf16_f32 v87, v152, v153
	s_nop 1
	v_mfma_f32_32x32x16_bf16 v[64:79], v[6:9], v[84:87], v[64:79]
	v_sub_f32_e32 v14, v96, v185
	v_sub_f32_e32 v15, v97, v185
	v_sub_f32_e32 v92, v104, v185
	v_sub_f32_e32 v93, v105, v185
	v_sub_f32_e32 v94, v106, v185
	v_sub_f32_e32 v95, v107, v185
	v_sub_f32_e32 v96, v108, v185
	v_sub_f32_e32 v97, v109, v185
	v_mfma_f32_32x32x16_bf16 v[48:63], v[10:13], v[84:87], v[48:63]
	v_sub_f32_e32 v84, v102, v185
	v_sub_f32_e32 v85, v103, v185
	v_exp_f32_e32 v14, v14
	v_exp_f32_e32 v15, v15
	v_exp_f32_e32 v90, v84
	v_exp_f32_e32 v91, v85
	v_exp_f32_e32 v84, v96
	v_mfma_f32_32x32x16_bf16 v[64:79], v[144:147], v[80:83], v[64:79]
	v_exp_f32_e32 v85, v97
	v_mfma_f32_32x32x16_bf16 v[48:63], v[2:5], v[80:83], v[48:63]
	v_sub_f32_e32 v80, v98, v185
	v_sub_f32_e32 v81, v99, v185
	v_sub_f32_e32 v82, v100, v185
	v_sub_f32_e32 v83, v101, v185
	v_exp_f32_e32 v86, v80
	v_exp_f32_e32 v87, v81
	v_exp_f32_e32 v88, v82
	v_exp_f32_e32 v89, v83
	v_exp_f32_e32 v80, v92
	v_exp_f32_e32 v81, v93
	v_exp_f32_e32 v82, v94
	v_exp_f32_e32 v83, v95
	v_add_f32_e32 v94, v14, v86
	v_add_f32_e32 v95, v15, v87
	v_sub_f32_e32 v98, v110, v185
	v_sub_f32_e32 v99, v111, v185
	v_add_f32_e32 v94, v88, v94
	v_add_f32_e32 v95, v89, v95
	v_exp_f32_e32 v92, v98
	v_exp_f32_e32 v93, v99
	v_add_f32_e32 v94, v90, v94
	v_add_f32_e32 v95, v91, v95
	s_nop 0
	v_add_f32_e32 v94, v80, v94
	v_add_f32_e32 v95, v81, v95
	v_cvt_pk_bf16_f32 v80, v80, v81
	v_add_f32_e32 v94, v82, v94
	v_add_f32_e32 v95, v83, v95
	v_cvt_pk_bf16_f32 v81, v82, v83
	v_add_f32_e32 v94, v84, v94
	v_add_f32_e32 v95, v85, v95
	v_cvt_pk_bf16_f32 v82, v84, v85
	v_add_f32_e32 v94, v92, v94
	v_add_f32_e32 v95, v93, v95
	v_cvt_pk_bf16_f32 v83, v92, v93
	v_add_f32_e32 v94, v94, v95
	v_add_f32_e32 v186, v0, v94
	v_cvt_pk_bf16_f32 v84, v14, v15
	v_cvt_pk_bf16_f32 v85, v86, v87
	v_cvt_pk_bf16_f32 v86, v88, v89
	v_cvt_pk_bf16_f32 v87, v90, v91
	s_nop 1
	v_mfma_f32_32x32x16_bf16 v[32:47], v[6:9], v[84:87], v[32:47]
	s_add_i32 s14, s14, 64
	v_add_u32_e32 v222, 64, v222
	v_add_u32_e32 v223, 64, v223
	s_cmp_lt_u32 s34, s38
	v_mfma_f32_32x32x16_bf16 v[16:31], v[10:13], v[84:87], v[16:31]
	v_mfma_f32_32x32x16_bf16 v[32:47], v[144:147], v[80:83], v[32:47]
	v_mfma_f32_32x32x16_bf16 v[16:31], v[2:5], v[80:83], v[16:31]
	s_cbranch_scc0 .LBB0_566
	s_mov_b32 s34, s40
	s_branch .LBB0_548

; __device__ __forceinline__ unsigned cvtpk_s(float lo, float hi) { f32x2 v = {lo, hi}; bf16x2_t b = __builtin_convertvector(v, bf16x2_t); return __builtin_bit_cast(unsigned, b); }
; __device__ __forceinline__ void softmax_tail(f32x16& s, HState& S, u32x4 (&pw)[2]) {
;     const float mn = S.m;
; #pragma unroll
;     for (int r = 0; r < 16; ++r) s[r] -= mn;
; #pragma unroll
;     for (int r = 0; r < 16; ++r) s[r] = __builtin_amdgcn_exp2f(s[r]);
;     float p0 = s[0], p1 = s[1];
; #pragma unroll
;     for (int r = 2; r < 16; r += 2) { p0 += s[r]; p1 += s[r + 1]; }
;     S.l += p0 + p1;
; #pragma unroll
;     for (int ks = 0; ks < 2; ++ks) { pw[ks].x = cvtpk_s(s[8 * ks + 0], s[8 * ks + 1]); pw[ks].y = cvtpk_s(s[8 * ks + 2], s[8 * ks + 3]); pw[ks].z = cvtpk_s(s[8 * ks + 4], s[8 * ks + 5]); pw[ks].w = cvtpk_s(s[8 * ks + 6], s[8 * ks + 7]); }
; }
; __device__ __forceinline__ void softmax_tile(f32x16& s, int kb, int lq, int radius, bool full, int hi, HState& S, u32x4 (&pw)[2]) { softmax_head(s, kb, lq, radius, full, hi, S); softmax_tail(s, S, pw); }
; __device__ __forceinline__ void pv_tile(const bf16x8 (&vf)[2][2], const u32x4 (&pw)[2], HState& S) {
; #pragma unroll
;     for (int ks = 0; ks < 2; ++ks)
; #pragma unroll
;         for (int dh = 0; dh < 2; ++dh) S.o[dh] = __builtin_amdgcn_mfma_f32_32x32x16_bf16(vf[ks][dh], __builtin_bit_cast(bf16x8, pw[ks]), S.o[dh], 0, 0, 0);
.LBB0_575:
	v_sub_f32_e32 v0, v80, v196
	v_sub_f32_e32 v14, v81, v196
	v_sub_f32_e32 v15, v82, v196
	v_sub_f32_e32 v80, v83, v196
	v_sub_f32_e32 v81, v84, v196
	v_sub_f32_e32 v82, v85, v196
	v_sub_f32_e32 v84, v87, v196
	v_sub_f32_e32 v87, v90, v196
	v_sub_f32_e32 v90, v93, v196
	v_exp_f32_e32 v0, v0
	v_exp_f32_e32 v14, v14
	v_exp_f32_e32 v15, v15
	v_exp_f32_e32 v93, v80
	v_sub_f32_e32 v83, v86, v196
	v_sub_f32_e32 v85, v88, v196
	v_sub_f32_e32 v86, v89, v196
	v_sub_f32_e32 v88, v91, v196
	v_sub_f32_e32 v89, v92, v196
	v_sub_f32_e32 v91, v94, v196
	v_sub_f32_e32 v92, v95, v196
	v_exp_f32_e32 v94, v81
	v_exp_f32_e32 v95, v82
	v_exp_f32_e32 v116, v83
	v_exp_f32_e32 v117, v84
	v_exp_f32_e32 v80, v85
	v_exp_f32_e32 v81, v86
	v_exp_f32_e32 v82, v87
	v_exp_f32_e32 v83, v88
	v_exp_f32_e32 v84, v89
	v_add_f32_e32 v88, v0, v15
	v_add_f32_e32 v89, v14, v93
	v_exp_f32_e32 v85, v90
	v_add_f32_e32 v88, v94, v88
	v_add_f32_e32 v89, v95, v89
	v_exp_f32_e32 v86, v91
	v_exp_f32_e32 v87, v92
	v_add_f32_e32 v88, v116, v88
	v_add_f32_e32 v89, v117, v89
	v_add_f32_e32 v88, v80, v88
	v_add_f32_e32 v89, v81, v89
	v_add_f32_e32 v88, v82, v88
	v_add_f32_e32 v89, v83, v89
	v_add_f32_e32 v88, v84, v88
	v_add_f32_e32 v89, v85, v89
	v_add_f32_e32 v88, v86, v88
	v_add_f32_e32 v89, v87, v89
	v_add_f32_e32 v88, v88, v89
	v_add_f32_e32 v207, v207, v88
	v_cvt_pk_bf16_f32 v80, v80, v81
	v_cvt_pk_bf16_f32 v81, v82, v83
	v_cvt_pk_bf16_f32 v82, v84, v85
	v_cvt_pk_bf16_f32 v83, v86, v87
	v_cvt_pk_bf16_f32 v84, v0, v14
	v_cvt_pk_bf16_f32 v85, v15, v93
	v_cvt_pk_bf16_f32 v86, v94, v95
	v_cvt_pk_bf16_f32 v87, v116, v117
	s_nop 1
	v_mfma_f32_32x32x16_bf16 v[64:79], v[2:5], v[84:87], v[64:79]
	v_sub_f32_e32 v0, v96, v185
	v_sub_f32_e32 v15, v97, v185
	v_sub_f32_e32 v92, v104, v185
	v_sub_f32_e32 v93, v105, v185
	v_sub_f32_e32 v94, v106, v185
	v_sub_f32_e32 v95, v107, v185
	v_sub_f32_e32 v96, v108, v185
	v_sub_f32_e32 v97, v109, v185
	v_mfma_f32_32x32x16_bf16 v[48:63], v[6:9], v[84:87], v[48:63]
	v_sub_f32_e32 v84, v102, v185
	v_sub_f32_e32 v85, v103, v185
	v_exp_f32_e32 v14, v0
	v_exp_f32_e32 v15, v15
	v_exp_f32_e32 v90, v84
	v_exp_f32_e32 v91, v85
	v_exp_f32_e32 v84, v96
	v_mfma_f32_32x32x16_bf16 v[64:79], v[10:13], v[80:83], v[64:79]
	v_exp_f32_e32 v85, v97
	v_mfma_f32_32x32x16_bf16 v[48:63], v[112:115], v[80:83], v[48:63]
	v_sub_f32_e32 v80, v98, v185
	v_sub_f32_e32 v81, v99, v185
	v_sub_f32_e32 v82, v100, v185
	v_sub_f32_e32 v83, v101, v185
	v_exp_f32_e32 v86, v80
	v_exp_f32_e32 v87, v81
	v_exp_f32_e32 v88, v82
	v_exp_f32_e32 v89, v83
	v_exp_f32_e32 v80, v92
	v_exp_f32_e32 v81, v93
	v_exp_f32_e32 v82, v94
	v_exp_f32_e32 v83, v95
	v_add_f32_e32 v94, v14, v86
	v_add_f32_e32 v95, v15, v87
	v_sub_f32_e32 v98, v110, v185
	v_sub_f32_e32 v99, v111, v185
	v_add_f32_e32 v94, v88, v94
	v_add_f32_e32 v95, v89, v95
	v_exp_f32_e32 v92, v98
	v_exp_f32_e32 v93, v99
	v_add_f32_e32 v94, v90, v94
	v_add_f32_e32 v95, v91, v95
	s_nop 0
	v_add_f32_e32 v94, v80, v94
	v_add_f32_e32 v95, v81, v95
	v_cvt_pk_bf16_f32 v80, v80, v81
	v_add_f32_e32 v94, v82, v94
	v_add_f32_e32 v95, v83, v95
	v_cvt_pk_bf16_f32 v81, v82, v83
	v_add_f32_e32 v94, v84, v94
	v_add_f32_e32 v95, v85, v95
	v_cvt_pk_bf16_f32 v82, v84, v85
	v_add_f32_e32 v94, v92, v94
	v_add_f32_e32 v95, v93, v95
	v_cvt_pk_bf16_f32 v83, v92, v93
	v_add_f32_e32 v0, v94, v95
	v_add_f32_e32 v186, v186, v0
	v_cvt_pk_bf16_f32 v84, v14, v15
	v_cvt_pk_bf16_f32 v85, v86, v87
	v_cvt_pk_bf16_f32 v86, v88, v89
	v_cvt_pk_bf16_f32 v87, v90, v91
	s_nop 1
	v_mfma_f32_32x32x16_bf16 v[32:47], v[2:5], v[84:87], v[32:47]
	v_mfma_f32_32x32x16_bf16 v[16:31], v[6:9], v[84:87], v[16:31]
	v_mfma_f32_32x32x16_bf16 v[32:47], v[10:13], v[80:83], v[32:47]
	v_mfma_f32_32x32x16_bf16 v[16:31], v[112:115], v[80:83], v[16:31]

; __device__ __forceinline__ unsigned cvtpk_s(float lo, float hi) { f32x2 v = {lo, hi}; bf16x2_t b = __builtin_convertvector(v, bf16x2_t); return __builtin_bit_cast(unsigned, b); }
; __device__ __forceinline__ void softmax_tail(f32x16& s, HState& S, u32x4 (&pw)[2]) {
;     const float mn = S.m;
; #pragma unroll
;     for (int r = 0; r < 16; ++r) s[r] -= mn;
; #pragma unroll
;     for (int r = 0; r < 16; ++r) s[r] = __builtin_amdgcn_exp2f(s[r]);
;     float p0 = s[0], p1 = s[1];
; #pragma unroll
;     for (int r = 2; r < 16; r += 2) { p0 += s[r]; p1 += s[r + 1]; }
;     S.l += p0 + p1;
; #pragma unroll
;     for (int ks = 0; ks < 2; ++ks) { pw[ks].x = cvtpk_s(s[8 * ks + 0], s[8 * ks + 1]); pw[ks].y = cvtpk_s(s[8 * ks + 2], s[8 * ks + 3]); pw[ks].z = cvtpk_s(s[8 * ks + 4], s[8 * ks + 5]); pw[ks].w = cvtpk_s(s[8 * ks + 6], s[8 * ks + 7]); }
; }
; __device__ __forceinline__ void softmax_tile(f32x16& s, int kb, int lq, int radius, bool full, int hi, HState& S, u32x4 (&pw)[2]) { softmax_head(s, kb, lq, radius, full, hi, S); softmax_tail(s, S, pw); }
; __device__ __forceinline__ void pv_tile(const bf16x8 (&vf)[2][2], const u32x4 (&pw)[2], HState& S) {
; #pragma unroll
;     for (int ks = 0; ks < 2; ++ks)
; #pragma unroll
;         for (int dh = 0; dh < 2; ++dh) S.o[dh] = __builtin_amdgcn_mfma_f32_32x32x16_bf16(vf[ks][dh], __builtin_bit_cast(bf16x8, pw[ks]), S.o[dh], 0, 0, 0);
.LBB0_586:
	v_sub_f32_e32 v80, v80, v196
	v_sub_f32_e32 v81, v81, v196
	v_sub_f32_e32 v82, v82, v196
	v_sub_f32_e32 v83, v83, v196
	v_sub_f32_e32 v135, v84, v196
	v_sub_f32_e32 v136, v85, v196
	v_sub_f32_e32 v137, v86, v196
	v_sub_f32_e32 v138, v87, v196
	v_sub_f32_e32 v139, v88, v196
	v_sub_f32_e32 v140, v89, v196
	v_sub_f32_e32 v141, v90, v196
	v_sub_f32_e32 v142, v91, v196
	v_exp_f32_e32 v84, v80
	v_exp_f32_e32 v85, v81
	v_exp_f32_e32 v86, v82
	v_exp_f32_e32 v87, v83
	v_exp_f32_e32 v88, v135
	v_exp_f32_e32 v89, v136
	v_exp_f32_e32 v90, v137
	v_exp_f32_e32 v91, v138
	v_cvt_pk_bf16_f32 v80, v84, v85
	v_cvt_pk_bf16_f32 v81, v86, v87
	v_cvt_pk_bf16_f32 v82, v88, v89
	v_cvt_pk_bf16_f32 v83, v90, v91
	v_sub_f32_e32 v143, v92, v196
	v_sub_f32_e32 v146, v93, v196
	s_waitcnt lgkmcnt(6)
	v_mfma_f32_32x32x16_bf16 v[64:79], v[128:131], v[80:83], v[64:79]
	v_sub_f32_e32 v147, v94, v196
	v_sub_f32_e32 v148, v95, v196
	v_exp_f32_e32 v92, v139
	v_exp_f32_e32 v93, v140
	v_exp_f32_e32 v94, v141
	v_exp_f32_e32 v95, v142
	v_exp_f32_e32 v128, v143
	s_waitcnt lgkmcnt(4)
	v_mfma_f32_32x32x16_bf16 v[48:63], v[124:127], v[80:83], v[48:63]
	v_exp_f32_e32 v129, v146
	v_exp_f32_e32 v130, v147
	v_exp_f32_e32 v131, v148
	v_add_f32_e32 v80, v84, v86
	v_add_f32_e32 v81, v85, v87
	v_cvt_pk_bf16_f32 v82, v128, v129
	v_add_f32_e32 v84, v88, v80
	v_add_f32_e32 v85, v89, v81
	v_cvt_pk_bf16_f32 v80, v92, v93
	v_cvt_pk_bf16_f32 v81, v94, v95
	v_cvt_pk_bf16_f32 v83, v130, v131
	v_add_f32_e32 v84, v90, v84
	v_add_f32_e32 v85, v91, v85
	s_add_i32 s39, s39, 64
	s_waitcnt lgkmcnt(2)
	v_mfma_f32_32x32x16_bf16 v[64:79], v[120:123], v[80:83], v[64:79]
	v_add_f32_e64 v84, v92, v84
	v_add_f32_e64 v85, v93, v85
	s_cmp_lt_i32 s40, s38
	v_add_f32_e64 v84, v94, v84
	v_add_f32_e64 v85, v95, v85
	v_add_u32_e32 v132, 0x1000, v132
	v_add_f32_e32 v84, v128, v84
	v_add_f32_e32 v85, v129, v85
	s_nop 0
	v_add_f32_e32 v84, v130, v84
	v_add_f32_e32 v85, v131, v85
	s_waitcnt lgkmcnt(0)
	v_mfma_f32_32x32x16_bf16 v[48:63], v[116:119], v[80:83], v[48:63]
	v_add_f32_e32 v84, v84, v85
	v_add_f32_e32 v207, v133, v84
	s_cbranch_scc0 .LBB0_588
	s_mov_b32 s40, s41
	s_branch .LBB0_578

; __device__ __forceinline__ unsigned cvtpk_s(float lo, float hi) { f32x2 v = {lo, hi}; bf16x2_t b = __builtin_convertvector(v, bf16x2_t); return __builtin_bit_cast(unsigned, b); }
; __device__ __forceinline__ void softmax_tail(f32x16& s, HState& S, u32x4 (&pw)[2]) {
;     const float mn = S.m;
; #pragma unroll
;     for (int r = 0; r < 16; ++r) s[r] -= mn;
; #pragma unroll
;     for (int r = 0; r < 16; ++r) s[r] = __builtin_amdgcn_exp2f(s[r]);
;     float p0 = s[0], p1 = s[1];
; #pragma unroll
;     for (int r = 2; r < 16; r += 2) { p0 += s[r]; p1 += s[r + 1]; }
;     S.l += p0 + p1;
; #pragma unroll
;     for (int ks = 0; ks < 2; ++ks) { pw[ks].x = cvtpk_s(s[8 * ks + 0], s[8 * ks + 1]); pw[ks].y = cvtpk_s(s[8 * ks + 2], s[8 * ks + 3]); pw[ks].z = cvtpk_s(s[8 * ks + 4], s[8 * ks + 5]); pw[ks].w = cvtpk_s(s[8 * ks + 6], s[8 * ks + 7]); }
; }
; __device__ __forceinline__ void softmax_tile(f32x16& s, int kb, int lq, int radius, bool full, int hi, HState& S, u32x4 (&pw)[2]) { softmax_head(s, kb, lq, radius, full, hi, S); softmax_tail(s, S, pw); }
; __device__ __forceinline__ void pv_tile(const bf16x8 (&vf)[2][2], const u32x4 (&pw)[2], HState& S) {
; #pragma unroll
;     for (int ks = 0; ks < 2; ++ks)
; #pragma unroll
;         for (int dh = 0; dh < 2; ++dh) S.o[dh] = __builtin_amdgcn_mfma_f32_32x32x16_bf16(vf[ks][dh], __builtin_bit_cast(bf16x8, pw[ks]), S.o[dh], 0, 0, 0);
.LBB0_593:
	v_sub_f32_e32 v80, v80, v196
	v_sub_f32_e32 v81, v81, v196
	v_sub_f32_e32 v82, v82, v196
	v_sub_f32_e32 v83, v83, v196
	v_sub_f32_e32 v100, v84, v196
	v_sub_f32_e32 v101, v85, v196
	v_sub_f32_e32 v102, v86, v196
	v_sub_f32_e32 v103, v87, v196
	v_sub_f32_e32 v104, v88, v196
	v_sub_f32_e32 v105, v89, v196
	v_sub_f32_e32 v106, v90, v196
	v_sub_f32_e32 v107, v91, v196
	v_exp_f32_e32 v84, v80
	v_exp_f32_e32 v85, v81
	v_exp_f32_e32 v86, v82
	v_exp_f32_e32 v87, v83
	v_exp_f32_e32 v88, v100
	v_exp_f32_e32 v89, v101
	v_exp_f32_e32 v90, v102
	v_exp_f32_e32 v91, v103
	v_cvt_pk_bf16_f32 v80, v84, v85
	v_cvt_pk_bf16_f32 v81, v86, v87
	v_cvt_pk_bf16_f32 v82, v88, v89
	v_cvt_pk_bf16_f32 v83, v90, v91
	v_sub_f32_e32 v108, v92, v196
	v_sub_f32_e32 v109, v93, v196
	s_waitcnt lgkmcnt(6)
	v_mfma_f32_32x32x16_bf16 v[64:79], v[96:99], v[80:83], v[64:79]
	v_sub_f32_e32 v110, v94, v196
	v_sub_f32_e32 v111, v95, v196
	v_exp_f32_e32 v92, v104
	v_exp_f32_e32 v93, v105
	v_exp_f32_e32 v94, v106
	v_exp_f32_e32 v95, v107
	v_exp_f32_e32 v96, v108
	s_waitcnt lgkmcnt(4)
	v_mfma_f32_32x32x16_bf16 v[48:63], v[10:13], v[80:83], v[48:63]
	v_exp_f32_e32 v97, v109
	v_exp_f32_e32 v98, v110
	v_exp_f32_e32 v99, v111
	v_add_f32_e32 v10, v84, v86
	v_add_f32_e32 v11, v85, v87
	v_cvt_pk_bf16_f32 v12, v96, v97
	v_add_f32_e32 v80, v88, v10
	v_add_f32_e32 v81, v89, v11
	v_cvt_pk_bf16_f32 v10, v92, v93
	v_cvt_pk_bf16_f32 v11, v94, v95
	v_cvt_pk_bf16_f32 v13, v98, v99
	s_waitcnt lgkmcnt(2)
	s_nop 0
	v_mfma_f32_32x32x16_bf16 v[64:79], v[6:9], v[10:13], v[64:79]
	v_add_f32_e64 v6, v90, v80
	v_add_f32_e64 v7, v91, v81
	v_add_f32_e64 v6, v92, v6
	v_add_f32_e64 v7, v93, v7
	v_add_f32_e64 v6, v94, v6
	v_add_f32_e64 v7, v95, v7
	v_add_f32_e32 v6, v96, v6
	v_add_f32_e32 v7, v97, v7
	s_waitcnt lgkmcnt(0)
	v_mfma_f32_32x32x16_bf16 v[48:63], v[2:5], v[10:13], v[48:63]
	v_add_f32_e64 v6, v98, v6
	v_add_f32_e64 v7, v99, v7
	v_add_f32_e32 v6, v6, v7
	v_add_f32_e32 v207, v207, v6

; __device__ __forceinline__ unsigned cvtpk_s(float lo, float hi) { f32x2 v = {lo, hi}; bf16x2_t b = __builtin_convertvector(v, bf16x2_t); return __builtin_bit_cast(unsigned, b); }
; __device__ __forceinline__ void softmax_tail(f32x16& s, HState& S, u32x4 (&pw)[2]) {
;     const float mn = S.m;
; #pragma unroll
;     for (int r = 0; r < 16; ++r) s[r] -= mn;
; #pragma unroll
;     for (int r = 0; r < 16; ++r) s[r] = __builtin_amdgcn_exp2f(s[r]);
;     float p0 = s[0], p1 = s[1];
; #pragma unroll
;     for (int r = 2; r < 16; r += 2) { p0 += s[r]; p1 += s[r + 1]; }
;     S.l += p0 + p1;
; #pragma unroll
;     for (int ks = 0; ks < 2; ++ks) { pw[ks].x = cvtpk_s(s[8 * ks + 0], s[8 * ks + 1]); pw[ks].y = cvtpk_s(s[8 * ks + 2], s[8 * ks + 3]); pw[ks].z = cvtpk_s(s[8 * ks + 4], s[8 * ks + 5]); pw[ks].w = cvtpk_s(s[8 * ks + 6], s[8 * ks + 7]); }
; }
; __device__ __forceinline__ void softmax_tile(f32x16& s, int kb, int lq, int radius, bool full, int hi, HState& S, u32x4 (&pw)[2]) { softmax_head(s, kb, lq, radius, full, hi, S); softmax_tail(s, S, pw); }
; __device__ __forceinline__ void pv_tile(const bf16x8 (&vf)[2][2], const u32x4 (&pw)[2], HState& S) {
; #pragma unroll
;     for (int ks = 0; ks < 2; ++ks)
; #pragma unroll
;         for (int dh = 0; dh < 2; ++dh) S.o[dh] = __builtin_amdgcn_mfma_f32_32x32x16_bf16(vf[ks][dh], __builtin_bit_cast(bf16x8, pw[ks]), S.o[dh], 0, 0, 0);
.LBB0_604:
	v_sub_f32_e32 v80, v80, v185
	v_sub_f32_e32 v81, v81, v185
	v_sub_f32_e32 v82, v82, v185
	v_sub_f32_e32 v83, v83, v185
	v_sub_f32_e32 v132, v84, v185
	v_sub_f32_e32 v133, v85, v185
	v_sub_f32_e32 v135, v86, v185
	v_sub_f32_e32 v136, v87, v185
	v_sub_f32_e32 v137, v88, v185
	v_sub_f32_e32 v138, v89, v185
	v_sub_f32_e32 v139, v90, v185
	v_sub_f32_e32 v140, v91, v185
	v_exp_f32_e32 v84, v80
	v_exp_f32_e32 v85, v81
	v_exp_f32_e32 v86, v82
	v_exp_f32_e32 v87, v83
	v_exp_f32_e32 v88, v132
	v_exp_f32_e32 v89, v133
	v_exp_f32_e32 v90, v135
	v_exp_f32_e32 v91, v136
	v_cvt_pk_bf16_f32 v80, v84, v85
	v_cvt_pk_bf16_f32 v81, v86, v87
	v_cvt_pk_bf16_f32 v82, v88, v89
	v_cvt_pk_bf16_f32 v83, v90, v91
	v_sub_f32_e32 v141, v92, v185
	v_sub_f32_e32 v142, v93, v185
	s_waitcnt lgkmcnt(6)
	v_mfma_f32_32x32x16_bf16 v[32:47], v[128:131], v[80:83], v[32:47]
	v_sub_f32_e32 v143, v94, v185
	v_sub_f32_e32 v146, v95, v185
	v_exp_f32_e32 v92, v137
	v_exp_f32_e32 v93, v138
	v_exp_f32_e32 v94, v139
	v_exp_f32_e32 v95, v140
	v_exp_f32_e32 v128, v141
	s_waitcnt lgkmcnt(4)
	v_mfma_f32_32x32x16_bf16 v[16:31], v[124:127], v[80:83], v[16:31]
	v_exp_f32_e32 v129, v142
	v_exp_f32_e32 v130, v143
	v_exp_f32_e32 v131, v146
	v_add_f32_e32 v80, v84, v86
	v_add_f32_e32 v81, v85, v87
	v_cvt_pk_bf16_f32 v82, v128, v129
	v_add_f32_e32 v84, v88, v80
	v_add_f32_e32 v85, v89, v81
	v_cvt_pk_bf16_f32 v80, v92, v93
	v_cvt_pk_bf16_f32 v81, v94, v95
	v_cvt_pk_bf16_f32 v83, v130, v131
	v_add_f32_e32 v84, v90, v84
	v_add_f32_e32 v85, v91, v85
	s_add_i32 s14, s14, 64
	s_waitcnt lgkmcnt(2)
	v_mfma_f32_32x32x16_bf16 v[32:47], v[120:123], v[80:83], v[32:47]
	v_add_f32_e64 v84, v92, v84
	v_add_f32_e64 v85, v93, v85
	s_cmp_lt_i32 s11, s19
	v_add_f32_e64 v84, v94, v84
	v_add_f32_e64 v85, v95, v85
	v_add_u32_e32 v14, 0x1000, v14
	v_add_f32_e32 v84, v128, v84
	v_add_f32_e32 v85, v129, v85
	s_nop 0
	v_add_f32_e32 v84, v130, v84
	v_add_f32_e32 v85, v131, v85
	s_waitcnt lgkmcnt(0)
	v_mfma_f32_32x32x16_bf16 v[16:31], v[116:119], v[80:83], v[16:31]
	v_add_f32_e32 v84, v84, v85
	v_add_f32_e32 v186, v15, v84
	s_cbranch_scc0 .LBB0_606
	s_mov_b32 s11, s12
	s_branch .LBB0_596

; __device__ __forceinline__ void pool_rows32(int row0, const bf16_t* proj, bf16_t* mix, int lane) {
;     ...
;     {
;         u32x4 v[16];
; #pragma unroll
;         for (int k = 0; k < 16; ++k) { const int off = k - 8, tt = t0 + off; const bool ok = (off >= -w2) && (off < w2) && (tt >= 0) && (tt < SEQ);
;             v[k] = (u32x4){0u, 0u, 0u, 0u}; if (ok) v[k] = *(const u32x4*)(base + (unsigned)tt * 1280u); }
; #pragma unroll
;         for (int k = 0; k < 16; ++k) { float f[8]; bf8_unpack(v[k], f);
; #pragma unroll
;             for (int i = 0; i < 8; ++i) S[i] += f[i]; }
;     }
.LBB0_653:
	s_or_b64 exec, exec, s[20:21]
	s_waitcnt vmcnt(0)
	v_lshlrev_b32_e32 v66, 16, v6
	v_and_b32_e32 v67, 0xffff0000, v6
	v_lshlrev_b32_e32 v6, 16, v7
	v_and_b32_e32 v7, 0xffff0000, v7
	v_lshlrev_b32_e32 v68, 16, v2
	v_and_b32_e32 v69, 0xffff0000, v2
	v_pk_add_f32 v[6:7], v[6:7], 0 op_sel_hi:[1,0]
	v_lshlrev_b32_e32 v2, 16, v3
	v_and_b32_e32 v3, 0xffff0000, v3
	v_add_f32_e32 v2, v6, v2
	v_add_f32_e32 v3, v7, v3
	v_lshlrev_b32_e32 v6, 16, v15
	v_and_b32_e32 v7, 0xffff0000, v15
	v_add_f32_e32 v2, v2, v6
	v_add_f32_e32 v3, v3, v7
	v_lshlrev_b32_e32 v6, 16, v11
	v_and_b32_e32 v7, 0xffff0000, v11
	v_pk_add_f32 v[66:67], v[66:67], 0 op_sel_hi:[1,0]
	v_add_f32_e32 v2, v2, v6
	v_add_f32_e32 v3, v3, v7
	v_lshlrev_b32_e32 v6, 16, v31
	v_and_b32_e32 v7, 0xffff0000, v31
	v_add_f32_e32 v66, v66, v68
	v_add_f32_e32 v67, v67, v69
	v_lshlrev_b32_e32 v68, 16, v14
	v_and_b32_e32 v69, 0xffff0000, v14
	v_add_f32_e32 v2, v2, v6
	v_add_f32_e32 v3, v3, v7
	v_lshlrev_b32_e32 v6, 16, v8
	v_and_b32_e32 v7, 0xffff0000, v8
	v_lshlrev_b32_e32 v8, 16, v9
	v_and_b32_e32 v9, 0xffff0000, v9
	v_add_f32_e32 v66, v66, v68
	v_add_f32_e32 v67, v67, v69
	v_lshlrev_b32_e32 v68, 16, v10
	v_and_b32_e32 v69, 0xffff0000, v10
	v_pk_add_f32 v[6:7], v[6:7], 0 op_sel_hi:[1,0]
	v_lshlrev_b32_e32 v10, 16, v4
	v_and_b32_e32 v11, 0xffff0000, v4
	v_pk_add_f32 v[8:9], v[8:9], 0 op_sel_hi:[1,0]
	v_lshlrev_b32_e32 v4, 16, v5
	v_and_b32_e32 v5, 0xffff0000, v5
	v_add_f32_e32 v6, v6, v10
	v_add_f32_e32 v7, v7, v11
	v_lshlrev_b32_e32 v10, 16, v16
	v_and_b32_e32 v11, 0xffff0000, v16
	v_add_f32_e32 v4, v8, v4
	v_add_f32_e32 v5, v9, v5
	v_lshlrev_b32_e32 v8, 16, v17
	v_and_b32_e32 v9, 0xffff0000, v17
	v_add_f32_e32 v6, v6, v10
	v_add_f32_e32 v7, v7, v11
	v_lshlrev_b32_e32 v10, 16, v12
	v_and_b32_e32 v11, 0xffff0000, v12
	v_add_f32_e32 v4, v4, v8
	v_add_f32_e32 v5, v5, v9
	v_lshlrev_b32_e32 v8, 16, v13
	v_and_b32_e32 v9, 0xffff0000, v13
	v_add_f32_e32 v66, v66, v68
	v_add_f32_e32 v67, v67, v69
	v_lshlrev_b32_e32 v68, 16, v30
	v_and_b32_e32 v69, 0xffff0000, v30
	v_add_f32_e32 v6, v6, v10
	v_add_f32_e32 v7, v7, v11
	v_lshlrev_b32_e32 v10, 16, v32
	v_and_b32_e32 v11, 0xffff0000, v32
	v_add_f32_e32 v4, v4, v8
	v_add_f32_e32 v5, v5, v9
	v_lshlrev_b32_e32 v8, 16, v33
	v_and_b32_e32 v9, 0xffff0000, v33
	v_add_f32_e32 v66, v66, v68
	v_add_f32_e32 v67, v67, v69
	v_add_f32_e32 v6, v6, v10
	v_add_f32_e32 v7, v7, v11
	v_add_f32_e32 v4, v4, v8
	v_add_f32_e32 v5, v5, v9
	v_lshlrev_b32_e32 v8, 16, v18
	v_and_b32_e32 v9, 0xffff0000, v18
	v_lshlrev_b32_e32 v10, 16, v19
	v_and_b32_e32 v11, 0xffff0000, v19
	v_lshlrev_b32_e32 v12, 16, v20
	v_and_b32_e32 v13, 0xffff0000, v20
	v_lshlrev_b32_e32 v14, 16, v21
	v_and_b32_e32 v15, 0xffff0000, v21
	v_lshlrev_b32_e32 v16, 16, v46
	v_and_b32_e32 v17, 0xffff0000, v46
	v_lshlrev_b32_e32 v18, 16, v47
	v_and_b32_e32 v19, 0xffff0000, v47
	v_lshlrev_b32_e32 v20, 16, v48
	v_and_b32_e32 v21, 0xffff0000, v48
	v_lshlrev_b32_e32 v30, 16, v49
	v_and_b32_e32 v31, 0xffff0000, v49
	v_add_f32_e32 v8, v66, v8
	v_add_f32_e32 v9, v67, v9
	v_add_f32_e32 v2, v2, v10
	v_add_f32_e32 v3, v3, v11
	v_add_f32_e32 v6, v6, v12
	v_add_f32_e32 v7, v7, v13
	v_add_f32_e32 v4, v4, v14
	v_add_f32_e32 v5, v5, v15
	v_lshlrev_b32_e32 v32, 16, v42
	v_and_b32_e32 v33, 0xffff0000, v42
	v_lshlrev_b32_e32 v42, 16, v43
	v_and_b32_e32 v43, 0xffff0000, v43
	v_lshlrev_b32_e32 v46, 16, v44
	v_and_b32_e32 v47, 0xffff0000, v44
	v_lshlrev_b32_e32 v44, 16, v45
	v_and_b32_e32 v45, 0xffff0000, v45
	v_add_f32_e32 v8, v8, v16
	v_add_f32_e32 v9, v9, v17
	v_add_f32_e32 v2, v2, v18
	v_add_f32_e32 v3, v3, v19
	v_add_f32_e32 v6, v6, v20
	v_add_f32_e32 v7, v7, v21
	v_add_f32_e32 v4, v4, v30
	v_add_f32_e32 v5, v5, v31
	v_add_f32_e32 v8, v8, v32
	v_add_f32_e32 v9, v9, v33
	v_lshlrev_b32_e32 v16, 16, v26
	v_and_b32_e32 v17, 0xffff0000, v26
	v_add_f32_e32 v2, v2, v42
	v_add_f32_e32 v3, v3, v43
	v_lshlrev_b32_e32 v10, 16, v27
	v_and_b32_e32 v11, 0xffff0000, v27
	v_add_f32_e32 v6, v6, v46
	v_add_f32_e32 v7, v7, v47
	v_lshlrev_b32_e32 v12, 16, v28
	v_and_b32_e32 v13, 0xffff0000, v28
	v_add_f32_e32 v4, v4, v44
	v_add_f32_e32 v5, v5, v45
	v_lshlrev_b32_e32 v14, 16, v29
	v_and_b32_e32 v15, 0xffff0000, v29
	v_add_f32_e32 v8, v8, v16
	v_add_f32_e32 v9, v9, v17
	v_lshlrev_b32_e32 v16, 16, v22
	v_and_b32_e32 v17, 0xffff0000, v22
	v_add_f32_e32 v2, v2, v10
	v_add_f32_e32 v3, v3, v11
	v_lshlrev_b32_e32 v10, 16, v23
	v_and_b32_e32 v11, 0xffff0000, v23
	v_add_f32_e32 v6, v6, v12
	v_add_f32_e32 v7, v7, v13
	v_lshlrev_b32_e32 v12, 16, v24
	v_and_b32_e32 v13, 0xffff0000, v24
	v_add_f32_e32 v4, v4, v14
	v_add_f32_e32 v5, v5, v15
	v_lshlrev_b32_e32 v14, 16, v25
	v_and_b32_e32 v15, 0xffff0000, v25
	s_bfe_u32 s5, s0, 0x70005
	v_add_f32_e32 v8, v8, v16
	v_add_f32_e32 v9, v9, v17
	v_lshlrev_b32_e32 v16, 16, v38
	v_and_b32_e32 v17, 0xffff0000, v38
	v_add_f32_e32 v2, v2, v10
	v_add_f32_e32 v3, v3, v11
	v_lshlrev_b32_e32 v10, 16, v39
	v_and_b32_e32 v11, 0xffff0000, v39
	v_add_f32_e32 v6, v6, v12
	v_add_f32_e32 v7, v7, v13
	v_lshlrev_b32_e32 v12, 16, v40
	v_and_b32_e32 v13, 0xffff0000, v40
	v_add_f32_e32 v4, v4, v14
	v_add_f32_e32 v5, v5, v15
	v_lshlrev_b32_e32 v14, 16, v41
	v_and_b32_e32 v15, 0xffff0000, v41
	s_lshl_b32 s6, s5, 5
	v_add_f32_e32 v8, v8, v16
	v_add_f32_e32 v9, v9, v17
	v_lshlrev_b32_e32 v16, 16, v34
	v_and_b32_e32 v17, 0xffff0000, v34
	v_add_f32_e32 v2, v2, v10
	v_add_f32_e32 v3, v3, v11
	v_lshlrev_b32_e32 v10, 16, v35
	v_and_b32_e32 v11, 0xffff0000, v35
	v_add_f32_e32 v6, v6, v12
	v_add_f32_e32 v7, v7, v13
	v_lshlrev_b32_e32 v12, 16, v36
	v_and_b32_e32 v13, 0xffff0000, v36
	v_add_f32_e32 v4, v4, v14
	v_add_f32_e32 v5, v5, v15
	v_lshlrev_b32_e32 v14, 16, v37
; __device__ __forceinline__ unsigned pk2(float lo, float hi) { return pg8::cvt_pk_bf16(lo, hi); }
; __device__ __forceinline__ void pool_rows32(int row0, const bf16_t* proj, bf16_t* mix, int lane) {
;     ...
;         for (int k = 0; k < 16; ++k) { const int off = k - 8, tt = t0 + off; const bool ok = (off >= -w2) && (off < w2) && (tt >= 0) && (tt < SEQ);
;             v[k] = (u32x4){0u, 0u, 0u, 0u}; if (ok) v[k] = *(const u32x4*)(base + (unsigned)tt * 1280u); }
; #pragma unroll
;         for (int k = 0; k < 16; ++k) { float f[8]; bf8_unpack(v[k], f);
; #pragma unroll
;             for (int i = 0; i < 8; ++i) S[i] += f[i]; }
;     ...
;         for (int r = 0; r < 8; ++r) { const int t = t0 + rb + r, te = t + w2, tl = t - w2;
;             vc[r] = *(const u32x4*)(base + (unsigned)t * 1280u);
;             ve[r] = (u32x4){0u, 0u, 0u, 0u}; if (te < SEQ) ve[r] = *(const u32x4*)(base + (unsigned)te * 1280u);
;             vl[r] = (u32x4){0u, 0u, 0u, 0u}; if (tl >= 0) vl[r] = *(const u32x4*)(base + (unsigned)tl * 1280u); }
; #pragma unroll
;         for (int r = 0; r < 8; ++r) { const int t = t0 + rb + r, lo = max(t - w2, 0), hi = min(t + w2, SEQ);
;             const float inv = 1.0f / (float)(hi - lo);
;             float c[8], d[8]; bf8_unpack(vc[r], c);
; #pragma unroll
;             for (int i = 0; i < 8; ++i) d[i] = S[i] * inv - c[i];
;             u32x4 w; w.x = pk2(d[0], d[1]); w.y = pk2(d[2], d[3]); w.z = pk2(d[4], d[5]); w.w = pk2(d[6], d[7]);
;             *(u32x4*)(mix + (size_t)(row0 + rb + r) * 1024 + 512 + 8 * lane) = w;
	v_and_b32_e32 v15, 0xffff0000, v37
	s_mul_i32 s1, s5, 0xa000
	v_add_u32_e32 v152, s6, v148
	v_add_u32_e32 v153, s6, v151
	s_mul_i32 s5, s5, 0x14000
	s_mul_hi_i32 s6, s4, 0xa00
	s_mulk_i32 s4, 0xa00
	v_add_f32_e32 v8, v8, v16
	v_add_f32_e32 v9, v9, v17
	v_lshlrev_b32_e32 v16, 16, v54
	v_and_b32_e32 v17, 0xffff0000, v54
	v_add_f32_e32 v2, v2, v10
	v_add_f32_e32 v3, v3, v11
	v_lshlrev_b32_e32 v10, 16, v55
	v_and_b32_e32 v11, 0xffff0000, v55
	v_add_f32_e32 v6, v6, v12
	v_add_f32_e32 v7, v7, v13
	v_lshlrev_b32_e32 v12, 16, v56
	v_and_b32_e32 v13, 0xffff0000, v56
	v_add_f32_e32 v4, v4, v14
	v_add_f32_e32 v5, v5, v15
	v_lshlrev_b32_e32 v14, 16, v57
	v_and_b32_e32 v15, 0xffff0000, v57
	s_add_u32 s4, s5, s4
	v_add_f32_e32 v8, v8, v16
	v_add_f32_e32 v9, v9, v17
	v_lshlrev_b32_e32 v16, 16, v50
	v_and_b32_e32 v17, 0xffff0000, v50
	v_add_f32_e32 v2, v2, v10
	v_add_f32_e32 v3, v3, v11
	v_lshlrev_b32_e32 v10, 16, v51
	v_and_b32_e32 v11, 0xffff0000, v51
	v_add_f32_e32 v6, v6, v12
	v_add_f32_e32 v7, v7, v13
	v_lshlrev_b32_e32 v12, 16, v52
	v_and_b32_e32 v13, 0xffff0000, v52
	v_add_f32_e32 v4, v4, v14
	v_add_f32_e32 v5, v5, v15
	v_lshlrev_b32_e32 v14, 16, v53
	v_and_b32_e32 v15, 0xffff0000, v53
	s_addc_u32 s5, 0, s6
	v_add_f32_e32 v8, v8, v16
	v_add_f32_e32 v9, v9, v17
	v_lshlrev_b32_e32 v16, 16, v62
	v_and_b32_e32 v17, 0xffff0000, v62
	v_add_f32_e32 v2, v2, v10
	v_add_f32_e32 v3, v3, v11
	v_lshlrev_b32_e32 v10, 16, v63
	v_and_b32_e32 v11, 0xffff0000, v63
	v_add_f32_e32 v6, v6, v12
	v_add_f32_e32 v7, v7, v13
	v_lshlrev_b32_e32 v12, 16, v64
	v_and_b32_e32 v13, 0xffff0000, v64
	v_add_f32_e32 v4, v4, v14
	v_add_f32_e32 v5, v5, v15
	v_lshlrev_b32_e32 v14, 16, v65
	v_and_b32_e32 v15, 0xffff0000, v65
	s_add_u32 s20, s68, s4
	v_add_f32_e32 v8, v8, v16
	v_add_f32_e32 v9, v9, v17
	v_lshlrev_b32_e32 v16, 16, v58
	v_and_b32_e32 v17, 0xffff0000, v58
	v_add_f32_e32 v2, v2, v10
	v_add_f32_e32 v3, v3, v11
	v_lshlrev_b32_e32 v10, 16, v59
	v_and_b32_e32 v11, 0xffff0000, v59
	v_add_f32_e32 v6, v6, v12
	v_add_f32_e32 v7, v7, v13
	v_lshlrev_b32_e32 v12, 16, v60
	v_and_b32_e32 v13, 0xffff0000, v60
	v_add_f32_e32 v4, v4, v14
	v_add_f32_e32 v5, v5, v15
	v_lshlrev_b32_e32 v14, 16, v61
	v_and_b32_e32 v15, 0xffff0000, v61
	s_addc_u32 s21, s69, s5
	v_add_f32_e32 v106, v8, v16
	v_add_f32_e32 v107, v9, v17
	v_add_f32_e32 v108, v2, v10
	v_add_f32_e32 v109, v3, v11
	v_add_f32_e32 v110, v6, v12
	v_add_f32_e32 v111, v7, v13
	v_add_f32_e32 v112, v4, v14
	v_add_f32_e32 v113, v5, v15
	s_mov_b32 s4, -8
	s_mov_b64 s[22:23], s[18:19]
	s_branch .LBB0_655
.LBB0_654:
	s_or_b64 exec, exec, s[28:29]
	v_max_i32_e32 v0, 0, v117
	v_min_i32_e32 v114, 0x1000, v116
	v_sub_u32_e32 v0, v114, v0
	v_cvt_f32_i32_e32 v0, v0
	s_waitcnt vmcnt(7)
	v_lshlrev_b32_e32 v117, 16, v26
	v_and_b32_e32 v26, 0xffff0000, v26
	v_lshlrev_b32_e32 v124, 16, v10
	v_div_scale_f32 v114, s[6:7], v0, v0, 1.0
	v_rcp_f32_e32 v116, v114
	v_div_scale_f32 v118, vcc, 1.0, v0, 1.0
	v_and_b32_e32 v125, 0xffff0000, v10
	v_fma_f32 v119, -v114, v116, 1.0
	v_fmac_f32_e32 v116, v119, v116
	v_mul_f32_e32 v119, v118, v116
	v_fma_f32 v121, -v114, v119, v118
	v_fmac_f32_e32 v119, v121, v116
	v_fma_f32 v114, -v114, v119, v118
	v_div_fmas_f32 v114, v114, v116, v119
	v_div_fixup_f32 v0, v114, v0, 1.0
	v_lshlrev_b32_e32 v114, 16, v27
	v_and_b32_e32 v27, 0xffff0000, v27
	v_lshlrev_b32_e32 v116, 16, v28
	v_and_b32_e32 v28, 0xffff0000, v28
	v_lshlrev_b32_e32 v118, 16, v29
	v_and_b32_e32 v29, 0xffff0000, v29
	v_fma_f32 v117, v106, v0, -v117
	v_fma_f32 v26, v107, v0, -v26
	v_fma_f32 v114, v108, v0, -v114
	v_fma_f32 v27, v109, v0, -v27
	v_fma_f32 v116, v110, v0, -v116
	v_fma_f32 v28, v111, v0, -v28
	v_fma_f32 v118, v112, v0, -v118
	v_fma_f32 v0, v113, v0, -v29
	v_cvt_pk_bf16_f32 v26, v117, v26
	v_cvt_pk_bf16_f32 v27, v114, v27
	v_cvt_pk_bf16_f32 v28, v116, v28
	v_cvt_pk_bf16_f32 v29, v118, v0
	v_max_i32_e32 v0, 0, v120
	v_min_i32_e32 v10, 0x1000, v115
	v_sub_u32_e32 v0, v10, v0
	v_cvt_f32_i32_e32 v0, v0
	v_lshlrev_b32_e32 v118, 16, v11
	v_and_b32_e32 v119, 0xffff0000, v11
	v_lshl_add_u64 v[116:117], s[22:23], 0, v[98:99]
	v_div_scale_f32 v10, s[6:7], v0, v0, 1.0
	v_rcp_f32_e32 v11, v10
	global_store_dwordx4 v[116:117], v[26:29], off
	v_lshlrev_b32_e32 v126, 16, v14
	v_and_b32_e32 v127, 0xffff0000, v14
	v_lshlrev_b32_e32 v28, 16, v12
	v_and_b32_e32 v29, 0xffff0000, v12
	v_fma_f32 v12, -v10, v11, 1.0
	v_fmac_f32_e32 v11, v12, v11
	v_div_scale_f32 v12, vcc, 1.0, v0, 1.0
	v_lshlrev_b32_e32 v26, 16, v13
	v_and_b32_e32 v27, 0xffff0000, v13
	v_mul_f32_e32 v13, v12, v11
	v_fma_f32 v14, -v10, v13, v12
	v_fmac_f32_e32 v13, v14, v11
	v_fma_f32 v10, -v10, v13, v12
	v_div_fmas_f32 v10, v10, v11, v13
	v_div_fixup_f32 v0, v10, v0, 1.0
	v_max_i32_e32 v10, 0, v129
	v_min_i32_e32 v11, 0x1000, v128
	v_sub_u32_e32 v10, v11, v10
	s_add_i32 s5, s0, s4
	v_cvt_f32_i32_e32 v10, v10
	s_add_i32 s6, s5, 9
	s_ashr_i32 s7, s6, 31
	s_lshl_b64 s[6:7], s[6:7], 11
	v_lshlrev_b32_e32 v116, 16, v15
	v_and_b32_e32 v117, 0xffff0000, v15
	v_lshl_add_u64 v[14:15], v[102:103], 0, s[6:7]
	v_div_scale_f32 v11, s[6:7], v10, v10, 1.0
	s_waitcnt vmcnt(7)
	v_lshlrev_b32_e32 v134, 16, v18
	v_and_b32_e32 v135, 0xffff0000, v18
	v_rcp_f32_e32 v18, v11
	v_lshlrev_b32_e32 v120, 16, v19
	v_and_b32_e32 v121, 0xffff0000, v19
	v_lshlrev_b32_e32 v12, 16, v24
	v_fma_f32 v19, -v11, v18, 1.0
	v_fmac_f32_e32 v18, v19, v18
	v_div_scale_f32 v19, vcc, 1.0, v10, 1.0
	v_and_b32_e32 v13, 0xffff0000, v24
	v_mul_f32_e32 v24, v19, v18
	v_lshlrev_b32_e32 v132, 16, v22
	v_and_b32_e32 v133, 0xffff0000, v22
	v_lshlrev_b32_e32 v122, 16, v23
	v_and_b32_e32 v123, 0xffff0000, v23
	v_lshlrev_b32_e32 v22, 16, v25
	v_and_b32_e32 v23, 0xffff0000, v25
	v_fma_f32 v25, -v11, v24, v19
	v_fmac_f32_e32 v24, v25, v18
	v_fma_f32 v11, -v11, v24, v19
	v_div_fmas_f32 v11, v11, v18, v24
	v_div_fixup_f32 v182, v11, v10, 1.0
	v_max_i32_e32 v10, 0, v137
	v_min_i32_e32 v11, 0x1000, v136
	v_sub_u32_e32 v10, v11, v10
	v_cvt_f32_i32_e32 v10, v10
	s_add_i32 s6, s5, 10
	s_ashr_i32 s7, s6, 31
	s_lshl_b64 s[6:7], s[6:7], 11
	v_lshl_add_u64 v[18:19], v[102:103], 0, s[6:7]
	v_div_scale_f32 v11, s[6:7], v10, v10, 1.0
	v_rcp_f32_e32 v24, v11
	s_waitcnt vmcnt(6)
; __device__ __forceinline__ unsigned pk2(float lo, float hi) { return pg8::cvt_pk_bf16(lo, hi); }
; __device__ __forceinline__ void pool_rows32(int row0, const bf16_t* proj, bf16_t* mix, int lane) {
;     ...
;         for (int r = 0; r < 8; ++r) { const int t = t0 + rb + r, lo = max(t - w2, 0), hi = min(t + w2, SEQ);
;             const float inv = 1.0f / (float)(hi - lo);
;             float c[8], d[8]; bf8_unpack(vc[r], c);
; #pragma unroll
;             for (int i = 0; i < 8; ++i) d[i] = S[i] * inv - c[i];
;             u32x4 w; w.x = pk2(d[0], d[1]); w.y = pk2(d[2], d[3]); w.z = pk2(d[4], d[5]); w.w = pk2(d[6], d[7]);
;             *(u32x4*)(mix + (size_t)(row0 + rb + r) * 1024 + 512 + 8 * lane) = w;
;             float e[8], l[8]; bf8_unpack(ve[r], e); bf8_unpack(vl[r], l);
; #pragma unroll
;             for (int i = 0; i < 8; ++i) S[i] += e[i] - l[i]; }
	v_lshlrev_b32_e32 v187, 16, v52
	v_and_b32_e32 v188, 0xffff0000, v52
	v_lshlrev_b32_e32 v189, 16, v53
	v_fma_f32 v25, -v11, v24, 1.0
	v_fmac_f32_e32 v24, v25, v24
	v_div_scale_f32 v25, vcc, 1.0, v10, 1.0
	v_and_b32_e32 v190, 0xffff0000, v53
	v_lshlrev_b32_e32 v52, 16, v32
	v_and_b32_e32 v53, 0xffff0000, v32
	v_mul_f32_e32 v32, v25, v24
	v_lshlrev_b32_e32 v142, 16, v30
	v_and_b32_e32 v143, 0xffff0000, v30
	v_lshlrev_b32_e32 v128, 16, v31
	v_and_b32_e32 v129, 0xffff0000, v31
	v_lshlrev_b32_e32 v30, 16, v33
	v_and_b32_e32 v31, 0xffff0000, v33
	v_fma_f32 v33, -v11, v32, v25
	v_fmac_f32_e32 v32, v33, v24
	v_fma_f32 v11, -v11, v32, v25
	v_div_fmas_f32 v11, v11, v24, v32
	v_div_fixup_f32 v191, v11, v10, 1.0
	v_max_i32_e32 v10, 0, v145
	v_min_i32_e32 v11, 0x1000, v144
	v_sub_u32_e32 v10, v11, v10
	v_cvt_f32_i32_e32 v10, v10
	s_add_i32 s6, s5, 11
	s_ashr_i32 s7, s6, 31
	s_lshl_b64 s[6:7], s[6:7], 11
	v_lshl_add_u64 v[24:25], v[102:103], 0, s[6:7]
	v_div_scale_f32 v11, s[6:7], v10, v10, 1.0
	v_rcp_f32_e32 v32, v11
	s_waitcnt vmcnt(5)
	v_lshlrev_b32_e32 v162, 16, v42
	v_and_b32_e32 v163, 0xffff0000, v42
	v_lshlrev_b32_e32 v136, 16, v43
	v_fma_f32 v33, -v11, v32, 1.0
	v_fmac_f32_e32 v32, v33, v32
	v_div_scale_f32 v33, vcc, 1.0, v10, 1.0
	v_mul_f32_e32 v42, v33, v32
	v_and_b32_e32 v137, 0xffff0000, v43
	v_fma_f32 v43, -v11, v42, v33
	v_fmac_f32_e32 v42, v43, v32
	v_fma_f32 v11, -v11, v42, v33
	v_div_fmas_f32 v11, v11, v32, v42
	v_div_fixup_f32 v200, v11, v10, 1.0
	v_max_i32_e32 v10, 0, v158
	v_min_i32_e32 v11, 0x1000, v156
	v_sub_u32_e32 v10, v11, v10
	v_cvt_f32_i32_e32 v10, v10
	s_add_i32 s6, s5, 12
	s_ashr_i32 s7, s6, 31
	s_lshl_b64 s[6:7], s[6:7], 11
	v_lshl_add_u64 v[32:33], v[102:103], 0, s[6:7]
	v_div_scale_f32 v11, s[6:7], v10, v10, 1.0
	v_rcp_f32_e32 v42, v11
	v_lshlrev_b32_e32 v192, 16, v62
	v_and_b32_e32 v193, 0xffff0000, v62
	v_lshlrev_b32_e32 v194, 16, v63
	v_fma_f32 v43, -v11, v42, 1.0
	v_fmac_f32_e32 v42, v43, v42
	v_div_scale_f32 v43, vcc, 1.0, v10, 1.0
	v_and_b32_e32 v195, 0xffff0000, v63
	v_lshlrev_b32_e32 v62, 16, v48
	v_and_b32_e32 v63, 0xffff0000, v48
	v_mul_f32_e32 v48, v43, v42
	v_lshlrev_b32_e32 v180, 16, v40
	v_and_b32_e32 v181, 0xffff0000, v40
	v_lshlrev_b32_e32 v154, 16, v41
	v_and_b32_e32 v155, 0xffff0000, v41
	v_lshlrev_b32_e32 v40, 16, v49
	v_and_b32_e32 v41, 0xffff0000, v49
	v_fma_f32 v49, -v11, v48, v43
	v_fmac_f32_e32 v48, v49, v42
	v_fma_f32 v11, -v11, v48, v43
	v_div_fmas_f32 v11, v11, v42, v48
	v_div_fixup_f32 v156, v11, v10, 1.0
	v_max_i32_e32 v10, 0, v168
	v_min_i32_e32 v11, 0x1000, v157
	v_sub_u32_e32 v10, v11, v10
	v_cvt_f32_i32_e32 v10, v10
	s_add_i32 s6, s5, 13
	s_ashr_i32 s7, s6, 31
	s_lshl_b64 s[6:7], s[6:7], 11
	v_lshl_add_u64 v[42:43], v[102:103], 0, s[6:7]
	v_div_scale_f32 v11, s[6:7], v10, v10, 1.0
	v_rcp_f32_e32 v48, v11
	s_waitcnt vmcnt(4)
	v_lshlrev_b32_e32 v164, 16, v58
	v_and_b32_e32 v165, 0xffff0000, v58
	v_lshlrev_b32_e32 v146, 16, v59
	v_fma_f32 v49, -v11, v48, 1.0
	v_fmac_f32_e32 v48, v49, v48
	v_div_scale_f32 v49, vcc, 1.0, v10, 1.0
	v_mul_f32_e32 v58, v49, v48
	v_and_b32_e32 v147, 0xffff0000, v59
	v_fma_f32 v59, -v11, v58, v49
	v_fmac_f32_e32 v58, v59, v48
	v_fma_f32 v11, -v11, v58, v49
	v_div_fmas_f32 v11, v11, v48, v58
	v_div_fixup_f32 v157, v11, v10, 1.0
	v_max_i32_e32 v10, 0, v169
	v_min_i32_e32 v11, 0x1000, v159
	v_sub_u32_e32 v10, v11, v10
	v_cvt_f32_i32_e32 v10, v10
	s_add_i32 s6, s5, 14
	s_ashr_i32 s7, s6, 31
	s_lshl_b64 s[6:7], s[6:7], 11
	v_lshl_add_u64 v[48:49], v[102:103], 0, s[6:7]
	v_div_scale_f32 v11, s[6:7], v10, v10, 1.0
	v_rcp_f32_e32 v58, v11
	s_waitcnt vmcnt(2)
	v_lshlrev_b32_e32 v220, 16, v92
	v_and_b32_e32 v221, 0xffff0000, v92
	v_lshlrev_b32_e32 v222, 16, v93
	v_fma_f32 v59, -v11, v58, 1.0
	v_fmac_f32_e32 v58, v59, v58
	v_div_scale_f32 v59, vcc, 1.0, v10, 1.0
	v_and_b32_e32 v223, 0xffff0000, v93
	v_lshlrev_b32_e32 v92, 16, v80
	v_and_b32_e32 v93, 0xffff0000, v80
	v_mul_f32_e32 v80, v59, v58
	v_lshlrev_b32_e32 v160, 16, v46
	v_and_b32_e32 v161, 0xffff0000, v46
	v_lshlrev_b32_e32 v138, 16, v47
	v_and_b32_e32 v139, 0xffff0000, v47
	v_lshlrev_b32_e32 v201, 16, v74
	v_and_b32_e32 v203, 0xffff0000, v74
	v_lshlrev_b32_e32 v204, 16, v75
	v_and_b32_e32 v205, 0xffff0000, v75
	v_lshlrev_b32_e32 v74, 16, v60
	v_and_b32_e32 v75, 0xffff0000, v60
	v_lshlrev_b32_e32 v46, 16, v61
	v_and_b32_e32 v47, 0xffff0000, v61
	v_lshlrev_b32_e32 v60, 16, v81
	v_and_b32_e32 v61, 0xffff0000, v81
	v_fma_f32 v81, -v11, v80, v59
	v_fmac_f32_e32 v80, v81, v58
	v_fma_f32 v11, -v11, v80, v59
	v_div_fmas_f32 v11, v11, v58, v80
	v_div_fixup_f32 v159, v11, v10, 1.0
	v_pk_add_f32 v[10:11], v[126:127], v[124:125] neg_lo:[0,1] neg_hi:[0,1]
	v_lshlrev_b32_e32 v176, 16, v38
	v_and_b32_e32 v177, 0xffff0000, v38
	v_lshlrev_b32_e32 v140, 16, v34
	v_and_b32_e32 v141, 0xffff0000, v34
	v_lshlrev_b32_e32 v170, 16, v66
	v_and_b32_e32 v171, 0xffff0000, v66
	v_lshlrev_b32_e32 v172, 16, v67
	v_and_b32_e32 v173, 0xffff0000, v67
	v_lshlrev_b32_e32 v168, 16, v90
	v_and_b32_e32 v217, 0xffff0000, v90
	v_lshlrev_b32_e32 v218, 16, v91
	v_and_b32_e32 v219, 0xffff0000, v91
	v_lshlrev_b32_e32 v90, 16, v84
	v_and_b32_e32 v91, 0xffff0000, v84
	v_lshlrev_b32_e32 v66, 16, v85
	v_and_b32_e32 v67, 0xffff0000, v85
	v_add_f32_e32 v80, v106, v10
	v_add_f32_e32 v81, v107, v11
	v_pk_add_f32 v[84:85], v[134:135], v[132:133] neg_lo:[0,1] neg_hi:[0,1]
	v_lshlrev_b32_e32 v183, 16, v50
	v_and_b32_e32 v184, 0xffff0000, v50
	v_fma_f32 v10, v0, v80, -v176
	v_fma_f32 v11, v0, v81, -v177
	v_add_f32_e32 v80, v80, v84
	v_add_f32_e32 v81, v81, v85
	v_pk_add_f32 v[84:85], v[142:143], v[140:141] neg_lo:[0,1] neg_hi:[0,1]
	v_lshlrev_b32_e32 v166, 16, v54
; __device__ __forceinline__ unsigned pk2(float lo, float hi) { return pg8::cvt_pk_bf16(lo, hi); }
; __device__ __forceinline__ void pool_rows32(int row0, const bf16_t* proj, bf16_t* mix, int lane) {
;     ...
;         for (int r = 0; r < 8; ++r) { const int t = t0 + rb + r, lo = max(t - w2, 0), hi = min(t + w2, SEQ);
;             const float inv = 1.0f / (float)(hi - lo);
;             float c[8], d[8]; bf8_unpack(vc[r], c);
; #pragma unroll
;             for (int i = 0; i < 8; ++i) d[i] = S[i] * inv - c[i];
;             u32x4 w; w.x = pk2(d[0], d[1]); w.y = pk2(d[2], d[3]); w.z = pk2(d[4], d[5]); w.w = pk2(d[6], d[7]);
;             *(u32x4*)(mix + (size_t)(row0 + rb + r) * 1024 + 512 + 8 * lane) = w;
;             float e[8], l[8]; bf8_unpack(ve[r], e); bf8_unpack(vl[r], l);
; #pragma unroll
;             for (int i = 0; i < 8; ++i) S[i] += e[i] - l[i]; }
	v_and_b32_e32 v167, 0xffff0000, v54
	v_fma_f32 v124, v182, v80, -v183
	v_fma_f32 v125, v182, v81, -v184
	v_add_f32_e32 v80, v80, v84
	v_add_f32_e32 v81, v81, v85
	v_pk_add_f32 v[84:85], v[162:163], v[160:161] neg_lo:[0,1] neg_hi:[0,1]
	v_lshlrev_b32_e32 v213, 16, v88
	v_and_b32_e32 v214, 0xffff0000, v88
	v_lshlrev_b32_e32 v215, 16, v89
	v_and_b32_e32 v216, 0xffff0000, v89
	v_lshlrev_b32_e32 v88, 16, v70
	v_and_b32_e32 v89, 0xffff0000, v70
	v_fma_f32 v126, v191, v80, -v192
	v_fma_f32 v127, v191, v81, -v193
	v_add_f32_e32 v80, v80, v84
	v_add_f32_e32 v81, v81, v85
	v_pk_add_f32 v[84:85], v[166:167], v[164:165] neg_lo:[0,1] neg_hi:[0,1]
	v_lshlrev_b32_e32 v185, 16, v51
	v_and_b32_e32 v186, 0xffff0000, v51
	v_lshlrev_b32_e32 v130, 16, v35
	v_and_b32_e32 v131, 0xffff0000, v35
	v_lshlrev_b32_e32 v50, 16, v36
	v_and_b32_e32 v51, 0xffff0000, v36
	v_lshlrev_b32_e32 v34, 16, v37
	v_and_b32_e32 v35, 0xffff0000, v37
	v_lshlrev_b32_e32 v196, 16, v64
	v_and_b32_e32 v197, 0xffff0000, v64
	v_lshlrev_b32_e32 v198, 16, v65
	v_and_b32_e32 v199, 0xffff0000, v65
	v_lshlrev_b32_e32 v64, 16, v44
	v_and_b32_e32 v65, 0xffff0000, v44
	v_lshlrev_b32_e32 v36, 16, v45
	v_and_b32_e32 v37, 0xffff0000, v45
	v_lshlrev_b32_e32 v206, 16, v76
	v_and_b32_e32 v207, 0xffff0000, v76
	v_lshlrev_b32_e32 v208, 16, v77
	v_and_b32_e32 v209, 0xffff0000, v77
	v_lshlrev_b32_e32 v144, 16, v55
	v_and_b32_e32 v145, 0xffff0000, v55
	v_lshlrev_b32_e32 v76, 16, v56
	v_and_b32_e32 v77, 0xffff0000, v56
	v_lshlrev_b32_e32 v44, 16, v57
	v_and_b32_e32 v45, 0xffff0000, v57
	v_lshlrev_b32_e32 v158, 16, v86
	v_and_b32_e32 v210, 0xffff0000, v86
	v_lshlrev_b32_e32 v211, 16, v87
	v_and_b32_e32 v212, 0xffff0000, v87
	v_lshlrev_b32_e32 v174, 16, v71
	v_and_b32_e32 v175, 0xffff0000, v71
	v_lshlrev_b32_e32 v70, 16, v72
	v_lshlrev_b32_e32 v86, 16, v68
	v_and_b32_e32 v71, 0xffff0000, v72
	v_and_b32_e32 v87, 0xffff0000, v68
	v_lshlrev_b32_e32 v54, 16, v69
	v_lshlrev_b32_e32 v56, 16, v73
	v_and_b32_e32 v57, 0xffff0000, v73
	v_and_b32_e32 v55, 0xffff0000, v69
	v_lshlrev_b32_e32 v68, 16, v82
	v_lshlrev_b32_e32 v72, 16, v78
	v_and_b32_e32 v69, 0xffff0000, v82
	v_and_b32_e32 v73, 0xffff0000, v78
	v_fma_f32 v132, v200, v80, -v201
	v_fma_f32 v133, v200, v81, -v203
	v_add_f32_e32 v80, v80, v84
	v_add_f32_e32 v81, v81, v85
	v_pk_add_f32 v[84:85], v[170:171], v[88:89] neg_lo:[0,1] neg_hi:[0,1]
	v_fma_f32 v134, v156, v80, -v158
	v_fma_f32 v135, v156, v81, -v210
	v_add_f32_e32 v80, v80, v84
	v_add_f32_e32 v81, v81, v85
	v_pk_add_f32 v[68:69], v[72:73], v[68:69] neg_lo:[0,1] neg_hi:[0,1]
	v_fma_f32 v84, v157, v80, -v168
	v_fma_f32 v85, v157, v81, -v217
	v_add_f32_e32 v68, v80, v68
	v_add_f32_e32 v69, v81, v69
	s_waitcnt vmcnt(1)
	v_lshlrev_b32_e32 v72, 16, v6
	v_and_b32_e32 v73, 0xffff0000, v6
	v_lshlrev_b32_e32 v80, 16, v2
	v_and_b32_e32 v81, 0xffff0000, v2
	v_lshlrev_b32_e32 v169, 16, v94
	v_and_b32_e32 v94, 0xffff0000, v94
	v_pk_add_f32 v[72:73], v[72:73], v[80:81] neg_lo:[0,1] neg_hi:[0,1]
	v_fma_f32 v88, v159, v68, -v169
	v_fma_f32 v89, v159, v69, -v94
	v_add_f32_e32 v106, v68, v72
	v_add_f32_e32 v107, v69, v73
	v_pk_add_f32 v[68:69], v[116:117], v[118:119] neg_lo:[0,1] neg_hi:[0,1]
	v_lshlrev_b32_e32 v178, 16, v39
	v_and_b32_e32 v179, 0xffff0000, v39
	v_add_f32_e32 v68, v108, v68
	v_add_f32_e32 v69, v109, v69
	v_pk_add_f32 v[72:73], v[120:121], v[122:123] neg_lo:[0,1] neg_hi:[0,1]
	v_cvt_pk_bf16_f32 v10, v10, v11
	v_fma_f32 v11, v0, v68, -v178
	v_fma_f32 v80, v0, v69, -v179
	v_add_f32_e32 v68, v68, v72
	v_add_f32_e32 v69, v69, v73
	v_pk_add_f32 v[72:73], v[128:129], v[130:131] neg_lo:[0,1] neg_hi:[0,1]
	v_fma_f32 v81, v182, v68, -v185
	v_fma_f32 v94, v182, v69, -v186
	v_add_f32_e32 v68, v68, v72
	v_add_f32_e32 v69, v69, v73
	v_pk_add_f32 v[72:73], v[136:137], v[138:139] neg_lo:[0,1] neg_hi:[0,1]
	v_fma_f32 v116, v191, v68, -v194
	v_fma_f32 v117, v191, v69, -v195
	v_add_f32_e32 v68, v68, v72
	v_add_f32_e32 v69, v69, v73
	v_pk_add_f32 v[72:73], v[144:145], v[146:147] neg_lo:[0,1] neg_hi:[0,1]
	v_lshlrev_b32_e32 v78, 16, v79
	v_lshlrev_b32_e32 v82, 16, v83
	v_and_b32_e32 v83, 0xffff0000, v83
	v_and_b32_e32 v79, 0xffff0000, v79
	v_fma_f32 v118, v200, v68, -v204
	v_fma_f32 v119, v200, v69, -v205
	v_add_f32_e32 v68, v68, v72
	v_add_f32_e32 v69, v69, v73
	v_pk_add_f32 v[72:73], v[172:173], v[174:175] neg_lo:[0,1] neg_hi:[0,1]
	v_fma_f32 v120, v156, v68, -v211
	v_fma_f32 v121, v156, v69, -v212
	v_add_f32_e32 v68, v68, v72
	v_add_f32_e32 v69, v69, v73
	v_pk_add_f32 v[72:73], v[78:79], v[82:83] neg_lo:[0,1] neg_hi:[0,1]
	v_lshlrev_b32_e32 v6, 16, v7
	v_and_b32_e32 v7, 0xffff0000, v7
	v_lshlrev_b32_e32 v2, 16, v3
	v_and_b32_e32 v3, 0xffff0000, v3
	v_lshlrev_b32_e32 v114, 16, v16
	v_and_b32_e32 v115, 0xffff0000, v16
	v_fma_f32 v122, v157, v68, -v218
	v_fma_f32 v123, v157, v69, -v219
	v_add_f32_e32 v68, v68, v72
	v_add_f32_e32 v69, v69, v73
	v_pk_add_f32 v[2:3], v[6:7], v[2:3] neg_lo:[0,1] neg_hi:[0,1]
	v_lshlrev_b32_e32 v38, 16, v20
	v_and_b32_e32 v39, 0xffff0000, v20
	v_add_f32_e32 v108, v68, v2
	v_add_f32_e32 v109, v69, v3
; __device__ __forceinline__ unsigned pk2(float lo, float hi) { return pg8::cvt_pk_bf16(lo, hi); }
; __device__ __forceinline__ void pool_rows32(int row0, const bf16_t* proj, bf16_t* mix, int lane) {
;     ...
;     for (int rb = 0; rb < 32; rb += 8) {
;         u32x4 ve[8], vl[8], vc[8];
; #pragma unroll
;         for (int r = 0; r < 8; ++r) { const int t = t0 + rb + r, te = t + w2, tl = t - w2;
;             vc[r] = *(const u32x4*)(base + (unsigned)t * 1280u);
;             ve[r] = (u32x4){0u, 0u, 0u, 0u}; if (te < SEQ) ve[r] = *(const u32x4*)(base + (unsigned)te * 1280u);
;             vl[r] = (u32x4){0u, 0u, 0u, 0u}; if (tl >= 0) vl[r] = *(const u32x4*)(base + (unsigned)tl * 1280u); }
; #pragma unroll
;         for (int r = 0; r < 8; ++r) { const int t = t0 + rb + r, lo = max(t - w2, 0), hi = min(t + w2, SEQ);
;             const float inv = 1.0f / (float)(hi - lo);
;             float c[8], d[8]; bf8_unpack(vc[r], c);
; #pragma unroll
;             for (int i = 0; i < 8; ++i) d[i] = S[i] * inv - c[i];
;             u32x4 w; w.x = pk2(d[0], d[1]); w.y = pk2(d[2], d[3]); w.z = pk2(d[4], d[5]); w.w = pk2(d[6], d[7]);
;             *(u32x4*)(mix + (size_t)(row0 + rb + r) * 1024 + 512 + 8 * lane) = w;
;             float e[8], l[8]; bf8_unpack(ve[r], e); bf8_unpack(vl[r], l);
; #pragma unroll
;             for (int i = 0; i < 8; ++i) S[i] += e[i] - l[i]; }
	v_pk_add_f32 v[2:3], v[114:115], v[28:29] neg_lo:[0,1] neg_hi:[0,1]
	v_lshlrev_b32_e32 v224, 16, v95
	v_and_b32_e32 v95, 0xffff0000, v95
	v_add_f32_e32 v2, v110, v2
	v_add_f32_e32 v3, v111, v3
	v_pk_add_f32 v[6:7], v[38:39], v[12:13] neg_lo:[0,1] neg_hi:[0,1]
	v_fma_f32 v72, v159, v68, -v224
	v_fma_f32 v73, v159, v69, -v95
	v_fma_f32 v68, v0, v2, -v180
	v_fma_f32 v69, v0, v3, -v181
	v_add_f32_e32 v2, v2, v6
	v_add_f32_e32 v3, v3, v7
	v_pk_add_f32 v[6:7], v[52:53], v[50:51] neg_lo:[0,1] neg_hi:[0,1]
	v_fma_f32 v38, v182, v2, -v187
	v_fma_f32 v39, v182, v3, -v188
	v_add_f32_e32 v2, v2, v6
	v_add_f32_e32 v3, v3, v7
	v_pk_add_f32 v[6:7], v[64:65], v[62:63] neg_lo:[0,1] neg_hi:[0,1]
	v_fma_f32 v50, v191, v2, -v196
	v_fma_f32 v51, v191, v3, -v197
	v_add_f32_e32 v2, v2, v6
	v_add_f32_e32 v3, v3, v7
	v_pk_add_f32 v[6:7], v[76:77], v[74:75] neg_lo:[0,1] neg_hi:[0,1]
	v_fma_f32 v52, v200, v2, -v206
	v_fma_f32 v53, v200, v3, -v207
	v_add_f32_e32 v2, v2, v6
	v_add_f32_e32 v3, v3, v7
	v_pk_add_f32 v[6:7], v[86:87], v[70:71] neg_lo:[0,1] neg_hi:[0,1]
	v_fma_f32 v62, v156, v2, -v213
	v_fma_f32 v63, v156, v3, -v214
	v_add_f32_e32 v2, v2, v6
	v_add_f32_e32 v3, v3, v7
	v_pk_add_f32 v[6:7], v[92:93], v[90:91] neg_lo:[0,1] neg_hi:[0,1]
	v_fma_f32 v64, v157, v2, -v220
	v_fma_f32 v65, v157, v3, -v221
	v_add_f32_e32 v2, v2, v6
	v_add_f32_e32 v3, v3, v7
	v_lshlrev_b32_e32 v6, 16, v8
	v_and_b32_e32 v7, 0xffff0000, v8
	v_lshlrev_b32_e32 v28, 16, v4
	v_and_b32_e32 v29, 0xffff0000, v4
	v_lshlrev_b32_e32 v16, 16, v17
	v_and_b32_e32 v17, 0xffff0000, v17
	v_lshlrev_b32_e32 v225, 16, v96
	v_and_b32_e32 v96, 0xffff0000, v96
	v_pk_add_f32 v[6:7], v[6:7], v[28:29] neg_lo:[0,1] neg_hi:[0,1]
	v_lshlrev_b32_e32 v20, 16, v21
	v_and_b32_e32 v21, 0xffff0000, v21
	v_fma_f32 v70, v159, v2, -v225
	v_fma_f32 v71, v159, v3, -v96
	v_add_f32_e32 v110, v2, v6
	v_add_f32_e32 v111, v3, v7
	v_pk_add_f32 v[2:3], v[16:17], v[26:27] neg_lo:[0,1] neg_hi:[0,1]
	v_pk_add_f32 v[6:7], v[20:21], v[22:23] neg_lo:[0,1] neg_hi:[0,1]
	v_add_f32_e32 v2, v112, v2
	v_add_f32_e32 v3, v113, v3
	s_add_i32 s6, s5, 15
	v_fma_f32 v4, v0, v2, -v154
	v_fma_f32 v0, v0, v3, -v155
	v_add_f32_e32 v2, v2, v6
	v_add_f32_e32 v3, v3, v7
	v_pk_add_f32 v[6:7], v[30:31], v[34:35] neg_lo:[0,1] neg_hi:[0,1]
	v_fma_f32 v20, v182, v2, -v189
	v_fma_f32 v21, v182, v3, -v190
	v_add_f32_e32 v2, v2, v6
	v_add_f32_e32 v3, v3, v7
	v_pk_add_f32 v[6:7], v[36:37], v[40:41] neg_lo:[0,1] neg_hi:[0,1]
	v_fma_f32 v22, v191, v2, -v198
	v_fma_f32 v23, v191, v3, -v199
	v_add_f32_e32 v2, v2, v6
	v_add_f32_e32 v3, v3, v7
	v_pk_add_f32 v[6:7], v[44:45], v[46:47] neg_lo:[0,1] neg_hi:[0,1]
	v_fma_f32 v26, v200, v2, -v208
	v_fma_f32 v27, v200, v3, -v209
	v_add_f32_e32 v2, v2, v6
	v_add_f32_e32 v3, v3, v7
	v_pk_add_f32 v[6:7], v[54:55], v[56:57] neg_lo:[0,1] neg_hi:[0,1]
	v_fma_f32 v28, v156, v2, -v215
	v_fma_f32 v29, v156, v3, -v216
	v_add_f32_e32 v2, v2, v6
	v_add_f32_e32 v3, v3, v7
	v_pk_add_f32 v[6:7], v[60:61], v[66:67] neg_lo:[0,1] neg_hi:[0,1]
	v_cvt_pk_bf16_f32 v11, v11, v80
	v_cvt_pk_bf16_f32 v12, v68, v69
	v_fma_f32 v30, v157, v2, -v222
	v_fma_f32 v31, v157, v3, -v223
	v_add_f32_e32 v6, v2, v6
	v_add_f32_e32 v7, v3, v7
	v_cvt_pk_bf16_f32 v13, v4, v0
	global_store_dwordx4 v[14:15], v[10:13], off offset:1024
	v_cvt_pk_bf16_f32 v2, v124, v125
	v_cvt_pk_bf16_f32 v3, v81, v94
	s_ashr_i32 s7, s6, 31
	v_lshlrev_b32_e32 v16, 16, v5
	v_and_b32_e32 v17, 0xffff0000, v5
	v_cvt_pk_bf16_f32 v4, v38, v39
	v_cvt_pk_bf16_f32 v5, v20, v21
	global_store_dwordx4 v[18:19], v[2:5], off offset:1024
	s_lshl_b64 s[6:7], s[6:7], 11
	s_add_i32 s4, s4, 8
	v_cvt_pk_bf16_f32 v2, v126, v127
	v_cvt_pk_bf16_f32 v3, v116, v117
	v_cvt_pk_bf16_f32 v4, v50, v51
	v_cvt_pk_bf16_f32 v5, v22, v23
	global_store_dwordx4 v[24:25], v[2:5], off offset:1024
	s_add_u32 s22, s22, 0x4000
	s_addc_u32 s23, s23, 0
	v_cvt_pk_bf16_f32 v2, v132, v133
	v_cvt_pk_bf16_f32 v3, v118, v119
	v_cvt_pk_bf16_f32 v4, v52, v53
	v_cvt_pk_bf16_f32 v5, v26, v27
	global_store_dwordx4 v[32:33], v[2:5], off offset:1024
	s_addk_i32 s1, 0x2800
	v_lshlrev_b32_e32 v226, 16, v97
	v_cvt_pk_bf16_f32 v2, v134, v135
	v_cvt_pk_bf16_f32 v3, v120, v121
	v_cvt_pk_bf16_f32 v4, v62, v63
	v_cvt_pk_bf16_f32 v5, v28, v29
	global_store_dwordx4 v[42:43], v[2:5], off offset:1024
	v_and_b32_e32 v97, 0xffff0000, v97
	v_lshl_add_u64 v[58:59], v[102:103], 0, s[6:7]
	v_cvt_pk_bf16_f32 v2, v84, v85
	v_cvt_pk_bf16_f32 v3, v122, v123
	v_lshlrev_b32_e32 v8, 16, v9
	v_and_b32_e32 v9, 0xffff0000, v9
	v_cvt_pk_bf16_f32 v4, v64, v65
	v_cvt_pk_bf16_f32 v5, v30, v31
	global_store_dwordx4 v[48:49], v[2:5], off offset:1024
	s_add_u32 s20, s20, 0x5000
	v_fma_f32 v34, v159, v6, -v226
	v_cvt_pk_bf16_f32 v2, v88, v89
	v_cvt_pk_bf16_f32 v3, v72, v73
	v_fma_f32 v35, v159, v7, -v97
	v_cvt_pk_bf16_f32 v4, v70, v71
	v_cvt_pk_bf16_f32 v5, v34, v35
	global_store_dwordx4 v[58:59], v[2:5], off offset:1024
	s_addc_u32 s21, s21, 0
	s_cmp_lt_u32 s4, 24
	v_pk_add_f32 v[2:3], v[8:9], v[16:17] neg_lo:[0,1] neg_hi:[0,1]
	s_nop 0
	v_add_f32_e32 v112, v6, v2
	v_add_f32_e32 v113, v7, v3
	s_cbranch_scc0 .LBB0_613
